# epilogue rsqrt: dead denormal-scaling branch of the rsqrtf expansion removed (argument >= 1e-6)
# baseline (speedup 1.0000x reference)
; #define LAS __attribute__((address_space(3)))
; template <int KIND>
; __device__ __forceinline__ void mini_task(const Ptrs& P, const bf16* A, int lda, const bf16* B, int ldb, int K, int row0, int cb, LAS unsigned char* lds) {
;     ...
;         for (int k = 0; k < kw; k += 64) {
;             bf16x8 a[4], b0[4], b1[4];
; #pragma unroll
;             for (int j = 0; j < 4; ++j) { a[j] = *(const bf16x8*)(ap + k + 16 * j); b0[j] = *(const bf16x8*)(bp + k + 16 * j); b1[j] = *(const bf16x8*)(bp + (size_t)32 * ldb + k + 16 * j); }
;             SBAR();
; #pragma unroll
;             for (int j = 0; j < 4; ++j) { c0 = __builtin_amdgcn_mfma_f32_32x32x16_bf16(a[j], b0[j], c0, 0, 0, 0); c1 = __builtin_amdgcn_mfma_f32_32x32x16_bf16(a[j], b1[j], c1, 0, 0, 0); } } }
;     LAS float* red = (LAS float*)lds + wave * 2048;
; #pragma unroll
;     for (int r = 0; r < 16; ++r) { const int rw = (r & 3) + 8 * (r >> 2) + 4 * hi; red[rw * 64 + r32] = c0[r]; red[rw * 64 + 32 + r32] = c1[r]; }
;     __syncthreads();
;     const int row = tid >> 4, cg = tid & 15;
;     f32x4 v = {0.f, 0.f, 0.f, 0.f};
; #pragma unroll
;     for (int w = 0; w < 8; ++w) v += *(const LAS f32x4*)((const LAS float*)lds + w * 2048 + row * 64 + cg * 4);
;     const int grow = row0 + row;
;     const bool meta = row0 >= MTOK;
;     if constexpr (KIND == MK_KR) {
;         v *= e_rs;
;         f32x4 o; { o[0] = __shfl_xor(v[0], 1); o[1] = __shfl_xor(v[1], 1); o[2] = __shfl_xor(v[2], 1); o[3] = __shfl_xor(v[3], 1); }
;         const int n = cg & 1, jp = cg >> 1; const f32x4 x1 = n ? o : v, x2 = n ? v : o;
;         if (!meta || row < NMETA) { const int pos = meta ? row : NMETA + (grow & 4095);
;             const f32x4 cs0 = e_cs0, cs1 = e_cs1;
;             const f32x4 cc = {cs0[0], cs0[2], cs1[0], cs1[2]}, sn = {cs0[1], cs0[3], cs1[1], cs1[3]};
;             const f32x4 ov = n ? (x2 * cc + x1 * sn) : (x1 * cc - x2 * sn);
;             u32x2 w; w.x = cvt_pk_bf16(ov[0], ov[1]); w.y = cvt_pk_bf16(ov[2], ov[3]);
;             bf16* d = P.kr_() + ((size_t)(meta ? 0 : (grow >> 12)) * LPAD + pos) * 64 + n * 32 + jp * 4; *(u32x2*)d = w;
;             if (meta) *(u32x2*)(d + (size_t)LPAD * 64) = w; }
;     } else if constexpr (KIND == MK_KVLAT) {
;         v *= e_rs;
;         u32x2 w; w.x = cvt_pk_bf16(v[0], v[1]); w.y = cvt_pk_bf16(v[2], v[3]);
;         *(u32x2*)(P.kvlat_() + (size_t)grow * 512 + cb * 64 + cg * 4) = w;
.LBB0_409:
	global_load_dword v36, v[40:41], off
	v_readfirstlane_b32 s12, v0
	s_and_b32 s8, s12, 0xffffffc0
	s_ashr_i32 s9, s8, 31
	s_lshl_b64 s[8:9], s[8:9], 1
	v_lshl_add_u64 v[6:7], v[38:39], 0, s[8:9]
	v_lshl_add_u64 v[8:9], v[42:43], 0, s[8:9]
	v_add_co_u32_e32 v10, vcc, 0x8000, v8
	s_nop 1
	v_addc_co_u32_e32 v11, vcc, 0, v9, vcc
	global_load_dwordx4 v[18:21], v[6:7], off
	global_load_dwordx4 v[48:51], v[6:7], off offset:32
	global_load_dwordx4 v[2:5], v[8:9], off
	global_load_dwordx4 v[52:55], v[8:9], off offset:32
	global_load_dwordx4 v[22:25], v[10:11], off
	global_load_dwordx4 v[56:59], v[10:11], off offset:32
	global_load_dwordx4 v[60:63], v[6:7], off offset:64
	global_load_dwordx4 v[66:69], v[6:7], off offset:96
	global_load_dwordx4 v[70:73], v[8:9], off offset:64
	global_load_dwordx4 v[74:77], v[8:9], off offset:96
	global_load_dwordx4 v[78:81], v[10:11], off offset:64
	global_load_dwordx4 v[82:85], v[10:11], off offset:96
	s_waitcnt vmcnt(9)
	v_mfma_f32_32x32x16_bf16 v[2:17], v[18:21], v[2:5], 0
	s_lshl_b32 s8, s12, 7
	s_and_b32 s8, s8, 0xffffe000
	v_add_u32_e32 v47, s8, v44
	s_waitcnt vmcnt(7)
	v_mfma_f32_32x32x16_bf16 v[18:33], v[18:21], v[22:25], 0
	v_mfma_f32_32x32x16_bf16 v[2:17], v[48:51], v[52:55], v[2:17]
	s_waitcnt vmcnt(6)
	v_mfma_f32_32x32x16_bf16 v[18:33], v[48:51], v[56:59], v[18:33]
	s_waitcnt vmcnt(3)
	v_mfma_f32_32x32x16_bf16 v[2:17], v[60:63], v[70:73], v[2:17]
	s_waitcnt vmcnt(1)
	v_mfma_f32_32x32x16_bf16 v[18:33], v[60:63], v[78:81], v[18:33]
	v_mfma_f32_32x32x16_bf16 v[2:17], v[66:69], v[74:77], v[2:17]
	s_waitcnt vmcnt(0)
	v_mfma_f32_32x32x16_bf16 v[18:33], v[66:69], v[82:85], v[18:33]
	s_nop 11
	ds_write2_b32 v47, v2, v18 offset1:32
	ds_write2_b32 v47, v3, v19 offset0:64 offset1:96
	ds_write2_b32 v47, v4, v20 offset0:128 offset1:160
	ds_write2_b32 v47, v5, v21 offset0:192 offset1:224
	v_add_u32_e32 v2, 0x800, v47
	ds_write2_b32 v2, v6, v22 offset1:32
	ds_write2_b32 v2, v7, v23 offset0:64 offset1:96
	ds_write2_b32 v2, v8, v24 offset0:128 offset1:160
	ds_write2_b32 v2, v9, v25 offset0:192 offset1:224
	v_add_u32_e32 v2, 0x1000, v47
	ds_write2_b32 v2, v10, v26 offset1:32
	ds_write2_b32 v2, v11, v27 offset0:64 offset1:96
	ds_write2_b32 v2, v12, v28 offset0:128 offset1:160
	ds_write2_b32 v2, v13, v29 offset0:192 offset1:224
	v_add_u32_e32 v2, 0x1800, v47
	ds_write2_b32 v2, v14, v30 offset1:32
	ds_write2_b32 v2, v15, v31 offset0:64 offset1:96
	ds_write2_b32 v2, v16, v32 offset0:128 offset1:160
	ds_write2_b32 v2, v17, v33 offset0:192 offset1:224
	s_waitcnt lgkmcnt(0)
	s_barrier
	s_and_saveexec_b64 s[8:9], s[0:1]
	s_cbranch_execz .LBB0_408
	ds_read_b128 v[2:5], v45
	ds_read_b128 v[6:9], v45 offset:8192
	ds_read_b128 v[10:13], v45 offset:16384
	ds_read_b128 v[14:17], v45 offset:24576
	s_ashr_i32 s14, s11, 2
	s_waitcnt lgkmcnt(3)
	v_pk_add_f32 v[4:5], v[4:5], 0 op_sel_hi:[1,0]
	v_pk_add_f32 v[2:3], v[2:3], 0 op_sel_hi:[1,0]
	s_waitcnt lgkmcnt(2)
	v_pk_add_f32 v[4:5], v[4:5], v[8:9]
	v_pk_add_f32 v[6:7], v[2:3], v[6:7]
	s_waitcnt lgkmcnt(1)
	v_pk_add_f32 v[8:9], v[4:5], v[12:13]
	ds_read_b128 v[2:5], v45 offset:32768
	v_pk_add_f32 v[10:11], v[6:7], v[10:11]
	s_waitcnt lgkmcnt(1)
	v_pk_add_f32 v[12:13], v[8:9], v[16:17]
	ds_read_b128 v[6:9], v45 offset:40960
	v_pk_add_f32 v[14:15], v[10:11], v[14:15]
	s_waitcnt lgkmcnt(1)
	v_pk_add_f32 v[4:5], v[12:13], v[4:5]
	ds_read_b128 v[10:13], v45 offset:49152
	v_pk_add_f32 v[2:3], v[14:15], v[2:3]
	s_waitcnt lgkmcnt(1)
	v_pk_add_f32 v[8:9], v[4:5], v[8:9]
	v_pk_add_f32 v[6:7], v[2:3], v[6:7]
	ds_read_b128 v[2:5], v45 offset:57344
	s_waitcnt lgkmcnt(1)
	v_pk_add_f32 v[8:9], v[8:9], v[12:13]
	v_fmamk_f32 v12, v36, 0x3b000000, v46
	v_pk_add_f32 v[6:7], v[6:7], v[10:11]
	s_waitcnt lgkmcnt(0)
	v_pk_add_f32 v[4:5], v[8:9], v[4:5]
	v_rsq_f32_e32 v12, v12
	v_pk_add_f32 v[2:3], v[6:7], v[2:3]
	s_bitcmp0_b32 s11, 1
	s_cselect_b32 s12, s10, 0xe200000
	v_mov_b32_e32 v6, v12
	v_pk_mul_f32 v[4:5], v[6:7], v[4:5] op_sel_hi:[0,1]
	v_pk_mul_f32 v[2:3], v[6:7], v[2:3] op_sel_hi:[0,1]
	s_mul_hi_i32 s15, s14, 0x1040
	s_mulk_i32 s14, 0x1040
	v_cvt_pk_bf16_f32 v2, v2, v3
	v_cvt_pk_bf16_f32 v3, v4, v5
	s_add_u32 s12, s86, s12
	v_mov_b32_e32 v5, s15
	v_or_b32_e32 v4, s14, v34
	s_addc_u32 s13, s87, 0
	v_lshlrev_b64 v[4:5], 8, v[4:5]
	v_and_or_b32 v6, s3, 64, v35
	v_lshl_add_u64 v[4:5], s[12:13], 0, v[4:5]
	v_lshlrev_b32_e32 v36, 1, v6
	v_lshl_add_u64 v[4:5], v[4:5], 0, v[36:37]
	global_store_dwordx2 v[4:5], v[2:3], off
	v_add_co_u32_e32 v4, vcc, 0x1040000, v4
	s_nop 1
	v_addc_co_u32_e32 v5, vcc, 0, v5, vcc
	global_store_dwordx2 v[4:5], v[2:3], off
	s_branch .LBB0_408

; __device__ __forceinline__ u32x4 pack8(const f32x4 a, const f32x4 b) { u32x4 w; w.x = cvt_pk_bf16(a[0], a[1]); w.y = cvt_pk_bf16(a[2], a[3]); w.z = cvt_pk_bf16(b[0], b[1]); w.w = cvt_pk_bf16(b[2], b[3]); return w; }
;     __device__ __forceinline__ void operator()(f32x4 (&acc)[2][2][4][2], const Unit& u, int wr, int wc, int fr, int fq) const {
;     ...
;                     for (int m = 0; m < 4; ++m) { const int row = ROWOF(ai, m);
;                         if (kind == K_QN) { const float sc = rsqrtf(rsv[ai * 4 + m] * (1.0f / 512.0f) + EPS) * QSCALE; const int b = row >> 12, i = row & 4095;
; #pragma unroll
;                             for (int bj = 0; bj < 2; ++bj) { const int h = u.pn * 2 + bj;
;                                 *(u32x4*)(P.q_() + ((size_t)(b * NH + h) * SEQ + i) * DQK + c8) = pack8(acc[ai][bj][m][0] * sc, acc[ai][bj][m][1] * sc); }
.LBB0_458:
	s_lshl_b32 s38, s57, 1
	s_add_i32 s38, s5, s38
	v_rsq_f32_e32 v130, v171
	s_ashr_i32 s39, s38, 31
	v_and_b32_e32 v140, 0xfcf, v166
	s_lshl_b64 s[40:41], s[38:39], 12
	v_mul_f32_e32 v134, 0x3dd53b94, v130
	v_pk_mul_f32 v[132:133], v[128:129], v[134:135] op_sel_hi:[1,0]
	v_pk_mul_f32 v[130:131], v[126:127], v[134:135] op_sel_hi:[1,0]
	v_pk_mul_f32 v[136:137], v[124:125], v[134:135] op_sel_hi:[1,0]
	v_pk_mul_f32 v[138:139], v[122:123], v[134:135] op_sel_hi:[1,0]
	v_or_b32_e32 v135, s40, v140
	v_cvt_pk_bf16_f32 v130, v130, v131
	v_cvt_pk_bf16_f32 v131, v132, v133
	v_cvt_pk_bf16_f32 v133, v136, v137
	v_mad_u64_u32 v[136:137], s[42:43], v135, s73, v[156:157]
	s_add_i32 s38, s38, 1
	v_cvt_pk_bf16_f32 v132, v138, v139
	v_mad_i32_i24 v137, s41, v183, v137
	s_ashr_i32 s39, s38, 31
	global_store_dwordx4 v[136:137], v[130:133], off
	v_pk_mul_f32 v[136:137], v[116:117], v[134:135] op_sel_hi:[1,0]
	s_lshl_b64 s[38:39], s[38:39], 12
	v_pk_mul_f32 v[132:133], v[120:121], v[134:135] op_sel_hi:[1,0]
	v_pk_mul_f32 v[130:131], v[118:119], v[134:135] op_sel_hi:[1,0]
	v_pk_mul_f32 v[134:135], v[114:115], v[134:135] op_sel_hi:[1,0]
	v_cvt_pk_bf16_f32 v130, v130, v131
	v_cvt_pk_bf16_f32 v131, v132, v133
	v_cvt_pk_bf16_f32 v132, v134, v135
	v_or_b32_e32 v134, s38, v140
	v_mad_u64_u32 v[134:135], s[40:41], v134, s73, v[156:157]
	v_cvt_pk_bf16_f32 v133, v136, v137
	v_mad_i32_i24 v135, s39, v183, v135
	global_store_dwordx4 v[134:135], v[130:133], off

; __device__ __forceinline__ u32x4 pack8(const f32x4 a, const f32x4 b) { u32x4 w; w.x = cvt_pk_bf16(a[0], a[1]); w.y = cvt_pk_bf16(a[2], a[3]); w.z = cvt_pk_bf16(b[0], b[1]); w.w = cvt_pk_bf16(b[2], b[3]); return w; }
;     __device__ __forceinline__ void operator()(f32x4 (&acc)[2][2][4][2], const Unit& u, int wr, int wc, int fr, int fq) const {
;     ...
;                     for (int m = 0; m < 4; ++m) { const int row = ROWOF(ai, m);
;                         if (kind == K_QN) { const float sc = rsqrtf(rsv[ai * 4 + m] * (1.0f / 512.0f) + EPS) * QSCALE; const int b = row >> 12, i = row & 4095;
; #pragma unroll
;                             for (int bj = 0; bj < 2; ++bj) { const int h = u.pn * 2 + bj;
;                                 *(u32x4*)(P.q_() + ((size_t)(b * NH + h) * SEQ + i) * DQK + c8) = pack8(acc[ai][bj][m][0] * sc, acc[ai][bj][m][1] * sc); }
.LBB0_463:
	s_lshl_b32 s38, s57, 1
	v_and_b32_e32 v140, 0xfdf, v130
	v_rsq_f32_e32 v131, v170
	s_add_i32 s38, s5, s38
	s_ashr_i32 s39, s38, 31
	s_lshl_b64 s[40:41], s[38:39], 12
	v_mov_b32_e32 v130, v131
	v_mul_f32_e32 v134, 0x3dd53b94, v130
	v_pk_mul_f32 v[132:133], v[112:113], v[134:135] op_sel_hi:[1,0]
	v_pk_mul_f32 v[130:131], v[110:111], v[134:135] op_sel_hi:[1,0]
	v_pk_mul_f32 v[136:137], v[108:109], v[134:135] op_sel_hi:[1,0]
	v_pk_mul_f32 v[138:139], v[106:107], v[134:135] op_sel_hi:[1,0]
	v_or_b32_e32 v135, s40, v140
	v_cvt_pk_bf16_f32 v130, v130, v131
	v_cvt_pk_bf16_f32 v131, v132, v133
	v_cvt_pk_bf16_f32 v133, v136, v137
	v_mad_u64_u32 v[136:137], s[42:43], v135, s73, v[156:157]
	s_add_i32 s38, s38, 1
	v_cvt_pk_bf16_f32 v132, v138, v139
	v_mad_i32_i24 v137, s41, v183, v137
	s_ashr_i32 s39, s38, 31
	global_store_dwordx4 v[136:137], v[130:133], off
	v_pk_mul_f32 v[136:137], v[100:101], v[134:135] op_sel_hi:[1,0]
	s_lshl_b64 s[38:39], s[38:39], 12
	v_pk_mul_f32 v[132:133], v[104:105], v[134:135] op_sel_hi:[1,0]
	v_pk_mul_f32 v[130:131], v[102:103], v[134:135] op_sel_hi:[1,0]
	v_pk_mul_f32 v[134:135], v[98:99], v[134:135] op_sel_hi:[1,0]
	v_cvt_pk_bf16_f32 v130, v130, v131
	v_cvt_pk_bf16_f32 v131, v132, v133
	v_cvt_pk_bf16_f32 v132, v134, v135
	v_or_b32_e32 v134, s38, v140
	v_mad_u64_u32 v[134:135], s[40:41], v134, s73, v[156:157]
	v_cvt_pk_bf16_f32 v133, v136, v137
	v_mad_i32_i24 v135, s39, v183, v135
	global_store_dwordx4 v[134:135], v[130:133], off

; __device__ __forceinline__ u32x4 pack8(const f32x4 a, const f32x4 b) { u32x4 w; w.x = cvt_pk_bf16(a[0], a[1]); w.y = cvt_pk_bf16(a[2], a[3]); w.z = cvt_pk_bf16(b[0], b[1]); w.w = cvt_pk_bf16(b[2], b[3]); return w; }
;     __device__ __forceinline__ void operator()(f32x4 (&acc)[2][2][4][2], const Unit& u, int wr, int wc, int fr, int fq) const {
;     ...
;                     for (int m = 0; m < 4; ++m) { const int row = ROWOF(ai, m);
;                         if (kind == K_QN) { const float sc = rsqrtf(rsv[ai * 4 + m] * (1.0f / 512.0f) + EPS) * QSCALE; const int b = row >> 12, i = row & 4095;
; #pragma unroll
;                             for (int bj = 0; bj < 2; ++bj) { const int h = u.pn * 2 + bj;
;                                 *(u32x4*)(P.q_() + ((size_t)(b * NH + h) * SEQ + i) * DQK + c8) = pack8(acc[ai][bj][m][0] * sc, acc[ai][bj][m][1] * sc); }
.LBB0_468:
	s_lshl_b32 s38, s57, 1
	v_and_b32_e32 v140, 0xfef, v130
	v_rsq_f32_e32 v131, v169
	s_add_i32 s38, s5, s38
	s_ashr_i32 s39, s38, 31
	s_lshl_b64 s[40:41], s[38:39], 12
	v_mov_b32_e32 v130, v131
	v_mul_f32_e32 v134, 0x3dd53b94, v130
	v_pk_mul_f32 v[132:133], v[96:97], v[134:135] op_sel_hi:[1,0]
	v_pk_mul_f32 v[130:131], v[94:95], v[134:135] op_sel_hi:[1,0]
	v_pk_mul_f32 v[136:137], v[92:93], v[134:135] op_sel_hi:[1,0]
	v_pk_mul_f32 v[138:139], v[90:91], v[134:135] op_sel_hi:[1,0]
	v_or_b32_e32 v135, s40, v140
	v_cvt_pk_bf16_f32 v130, v130, v131
	v_cvt_pk_bf16_f32 v131, v132, v133
	v_cvt_pk_bf16_f32 v133, v136, v137
	v_mad_u64_u32 v[136:137], s[42:43], v135, s73, v[156:157]
	s_add_i32 s38, s38, 1
	v_cvt_pk_bf16_f32 v132, v138, v139
	v_mad_i32_i24 v137, s41, v183, v137
	s_ashr_i32 s39, s38, 31
	global_store_dwordx4 v[136:137], v[130:133], off
	v_pk_mul_f32 v[136:137], v[84:85], v[134:135] op_sel_hi:[1,0]
	s_lshl_b64 s[38:39], s[38:39], 12
	v_pk_mul_f32 v[132:133], v[88:89], v[134:135] op_sel_hi:[1,0]
	v_pk_mul_f32 v[130:131], v[86:87], v[134:135] op_sel_hi:[1,0]
	v_pk_mul_f32 v[134:135], v[82:83], v[134:135] op_sel_hi:[1,0]
	v_cvt_pk_bf16_f32 v130, v130, v131
	v_cvt_pk_bf16_f32 v131, v132, v133
	v_cvt_pk_bf16_f32 v132, v134, v135
	v_or_b32_e32 v134, s38, v140
	v_mad_u64_u32 v[134:135], s[40:41], v134, s73, v[156:157]
	v_cvt_pk_bf16_f32 v133, v136, v137
	v_mad_i32_i24 v135, s39, v183, v135
	global_store_dwordx4 v[134:135], v[130:133], off

; __device__ __forceinline__ u32x4 pack8(const f32x4 a, const f32x4 b) { u32x4 w; w.x = cvt_pk_bf16(a[0], a[1]); w.y = cvt_pk_bf16(a[2], a[3]); w.z = cvt_pk_bf16(b[0], b[1]); w.w = cvt_pk_bf16(b[2], b[3]); return w; }
;     __device__ __forceinline__ void operator()(f32x4 (&acc)[2][2][4][2], const Unit& u, int wr, int wc, int fr, int fq) const {
;     ...
;                     for (int m = 0; m < 4; ++m) { const int row = ROWOF(ai, m);
;                         if (kind == K_QN) { const float sc = rsqrtf(rsv[ai * 4 + m] * (1.0f / 512.0f) + EPS) * QSCALE; const int b = row >> 12, i = row & 4095;
; #pragma unroll
;                             for (int bj = 0; bj < 2; ++bj) { const int h = u.pn * 2 + bj;
;                                 *(u32x4*)(P.q_() + ((size_t)(b * NH + h) * SEQ + i) * DQK + c8) = pack8(acc[ai][bj][m][0] * sc, acc[ai][bj][m][1] * sc); }
.LBB0_473:
	s_lshl_b32 s38, s57, 1
	v_and_b32_e32 v140, 0xfff, v130
	v_rsq_f32_e32 v131, v168
	s_add_i32 s38, s5, s38
	s_ashr_i32 s39, s38, 31
	s_lshl_b64 s[40:41], s[38:39], 12
	v_mov_b32_e32 v130, v131
	v_mul_f32_e32 v134, 0x3dd53b94, v130
	v_pk_mul_f32 v[132:133], v[80:81], v[134:135] op_sel_hi:[1,0]
	v_pk_mul_f32 v[130:131], v[78:79], v[134:135] op_sel_hi:[1,0]
	v_pk_mul_f32 v[136:137], v[76:77], v[134:135] op_sel_hi:[1,0]
	v_pk_mul_f32 v[138:139], v[74:75], v[134:135] op_sel_hi:[1,0]
	v_or_b32_e32 v135, s40, v140
	v_cvt_pk_bf16_f32 v130, v130, v131
	v_cvt_pk_bf16_f32 v131, v132, v133
	v_cvt_pk_bf16_f32 v133, v136, v137
	v_mad_u64_u32 v[136:137], s[42:43], v135, s73, v[156:157]
	s_add_i32 s38, s38, 1
	v_cvt_pk_bf16_f32 v132, v138, v139
	v_mad_i32_i24 v137, s41, v183, v137
	s_ashr_i32 s39, s38, 31
	global_store_dwordx4 v[136:137], v[130:133], off
	v_pk_mul_f32 v[136:137], v[68:69], v[134:135] op_sel_hi:[1,0]
	s_lshl_b64 s[38:39], s[38:39], 12
	v_pk_mul_f32 v[132:133], v[72:73], v[134:135] op_sel_hi:[1,0]
	v_pk_mul_f32 v[130:131], v[70:71], v[134:135] op_sel_hi:[1,0]
	v_pk_mul_f32 v[134:135], v[66:67], v[134:135] op_sel_hi:[1,0]
	v_cvt_pk_bf16_f32 v130, v130, v131
	v_cvt_pk_bf16_f32 v131, v132, v133
	v_cvt_pk_bf16_f32 v132, v134, v135
	v_or_b32_e32 v134, s38, v140
	v_mad_u64_u32 v[134:135], s[40:41], v134, s73, v[156:157]
	v_cvt_pk_bf16_f32 v133, v136, v137
	v_mad_i32_i24 v135, s39, v183, v135
	global_store_dwordx4 v[134:135], v[130:133], off

; __device__ __forceinline__ u32x4 pack8(const f32x4 a, const f32x4 b) { u32x4 w; w.x = cvt_pk_bf16(a[0], a[1]); w.y = cvt_pk_bf16(a[2], a[3]); w.z = cvt_pk_bf16(b[0], b[1]); w.w = cvt_pk_bf16(b[2], b[3]); return w; }
;     __device__ __forceinline__ void operator()(f32x4 (&acc)[2][2][4][2], const Unit& u, int wr, int wc, int fr, int fq) const {
;     ...
;                     for (int m = 0; m < 4; ++m) { const int row = ROWOF(ai, m);
;                         if (kind == K_QN) { const float sc = rsqrtf(rsv[ai * 4 + m] * (1.0f / 512.0f) + EPS) * QSCALE; const int b = row >> 12, i = row & 4095;
; #pragma unroll
;                             for (int bj = 0; bj < 2; ++bj) { const int h = u.pn * 2 + bj;
;                                 *(u32x4*)(P.q_() + ((size_t)(b * NH + h) * SEQ + i) * DQK + c8) = pack8(acc[ai][bj][m][0] * sc, acc[ai][bj][m][1] * sc); }
.LBB0_478:
	v_and_b32_e32 v144, 0xfcf, v131
	s_nop 0
	v_rsq_f32_e32 v133, v165
	s_nop 0
	v_mov_b32_e32 v131, v133
	v_mul_f32_e32 v138, 0x3dd53b94, v131
	v_pk_mul_f32 v[136:137], v[64:65], v[138:139] op_sel_hi:[1,0]
	v_pk_mul_f32 v[134:135], v[62:63], v[138:139] op_sel_hi:[1,0]
	v_pk_mul_f32 v[140:141], v[60:61], v[138:139] op_sel_hi:[1,0]
	v_ashrrev_i32_e32 v131, 31, v130
	v_cvt_pk_bf16_f32 v134, v134, v135
	v_cvt_pk_bf16_f32 v135, v136, v137
	v_cvt_pk_bf16_f32 v137, v140, v141
	v_lshlrev_b64 v[140:141], 12, v[130:131]
	v_pk_mul_f32 v[142:143], v[58:59], v[138:139] op_sel_hi:[1,0]
	v_or_b32_e32 v131, v140, v144
	v_cvt_pk_bf16_f32 v136, v142, v143
	v_mad_u64_u32 v[142:143], s[38:39], v131, s73, v[156:157]
	v_mad_i32_i24 v143, v141, s73, v143
	global_store_dwordx4 v[142:143], v[134:137], off
	v_pk_mul_f32 v[140:141], v[52:53], v[138:139] op_sel_hi:[1,0]
	s_nop 0
	v_pk_mul_f32 v[136:137], v[56:57], v[138:139] op_sel_hi:[1,0]
	v_pk_mul_f32 v[134:135], v[54:55], v[138:139] op_sel_hi:[1,0]
	v_pk_mul_f32 v[138:139], v[50:51], v[138:139] op_sel_hi:[1,0]
	v_cvt_pk_bf16_f32 v134, v134, v135
	v_cvt_pk_bf16_f32 v135, v136, v137
	v_cvt_pk_bf16_f32 v136, v138, v139
	v_add_u32_e32 v138, 1, v130
	v_ashrrev_i32_e32 v139, 31, v138
	v_lshlrev_b64 v[138:139], 12, v[138:139]
	v_or_b32_e32 v131, v138, v144
	v_cvt_pk_bf16_f32 v137, v140, v141
	v_mad_u64_u32 v[140:141], s[38:39], v131, s73, v[156:157]
	v_mad_i32_i24 v141, v139, s73, v141
	global_store_dwordx4 v[140:141], v[134:137], off

; __device__ __forceinline__ u32x4 pack8(const f32x4 a, const f32x4 b) { u32x4 w; w.x = cvt_pk_bf16(a[0], a[1]); w.y = cvt_pk_bf16(a[2], a[3]); w.z = cvt_pk_bf16(b[0], b[1]); w.w = cvt_pk_bf16(b[2], b[3]); return w; }
;     __device__ __forceinline__ void operator()(f32x4 (&acc)[2][2][4][2], const Unit& u, int wr, int wc, int fr, int fq) const {
;     ...
;                     for (int m = 0; m < 4; ++m) { const int row = ROWOF(ai, m);
;                         if (kind == K_QN) { const float sc = rsqrtf(rsv[ai * 4 + m] * (1.0f / 512.0f) + EPS) * QSCALE; const int b = row >> 12, i = row & 4095;
; #pragma unroll
;                             for (int bj = 0; bj < 2; ++bj) { const int h = u.pn * 2 + bj;
;                                 *(u32x4*)(P.q_() + ((size_t)(b * NH + h) * SEQ + i) * DQK + c8) = pack8(acc[ai][bj][m][0] * sc, acc[ai][bj][m][1] * sc); }
.LBB0_483:
	v_and_b32_e32 v144, 0xfdf, v131
	s_nop 0
	v_rsq_f32_e32 v133, v164
	s_nop 0
	v_mov_b32_e32 v131, v133
	v_mul_f32_e32 v138, 0x3dd53b94, v131
	v_pk_mul_f32 v[136:137], v[48:49], v[138:139] op_sel_hi:[1,0]
	v_pk_mul_f32 v[134:135], v[46:47], v[138:139] op_sel_hi:[1,0]
	v_pk_mul_f32 v[140:141], v[44:45], v[138:139] op_sel_hi:[1,0]
	v_ashrrev_i32_e32 v131, 31, v130
	v_cvt_pk_bf16_f32 v134, v134, v135
	v_cvt_pk_bf16_f32 v135, v136, v137
	v_cvt_pk_bf16_f32 v137, v140, v141
	v_lshlrev_b64 v[140:141], 12, v[130:131]
	v_pk_mul_f32 v[142:143], v[42:43], v[138:139] op_sel_hi:[1,0]
	v_or_b32_e32 v131, v140, v144
	v_cvt_pk_bf16_f32 v136, v142, v143
	v_mad_u64_u32 v[142:143], s[38:39], v131, s73, v[156:157]
	v_mad_i32_i24 v143, v141, s73, v143
	global_store_dwordx4 v[142:143], v[134:137], off
	v_pk_mul_f32 v[140:141], v[36:37], v[138:139] op_sel_hi:[1,0]
	s_nop 0
	v_pk_mul_f32 v[136:137], v[40:41], v[138:139] op_sel_hi:[1,0]
	v_pk_mul_f32 v[134:135], v[38:39], v[138:139] op_sel_hi:[1,0]
	v_pk_mul_f32 v[138:139], v[34:35], v[138:139] op_sel_hi:[1,0]
	v_cvt_pk_bf16_f32 v134, v134, v135
	v_cvt_pk_bf16_f32 v135, v136, v137
	v_cvt_pk_bf16_f32 v136, v138, v139
	v_add_u32_e32 v138, 1, v130
	v_ashrrev_i32_e32 v139, 31, v138
	v_lshlrev_b64 v[138:139], 12, v[138:139]
	v_or_b32_e32 v131, v138, v144
	v_cvt_pk_bf16_f32 v137, v140, v141
	v_mad_u64_u32 v[140:141], s[38:39], v131, s73, v[156:157]
	v_mad_i32_i24 v141, v139, s73, v141
	global_store_dwordx4 v[140:141], v[134:137], off

; __device__ __forceinline__ u32x4 pack8(const f32x4 a, const f32x4 b) { u32x4 w; w.x = cvt_pk_bf16(a[0], a[1]); w.y = cvt_pk_bf16(a[2], a[3]); w.z = cvt_pk_bf16(b[0], b[1]); w.w = cvt_pk_bf16(b[2], b[3]); return w; }
;     __device__ __forceinline__ void operator()(f32x4 (&acc)[2][2][4][2], const Unit& u, int wr, int wc, int fr, int fq) const {
;     ...
;                     for (int m = 0; m < 4; ++m) { const int row = ROWOF(ai, m);
;                         if (kind == K_QN) { const float sc = rsqrtf(rsv[ai * 4 + m] * (1.0f / 512.0f) + EPS) * QSCALE; const int b = row >> 12, i = row & 4095;
; #pragma unroll
;                             for (int bj = 0; bj < 2; ++bj) { const int h = u.pn * 2 + bj;
;                                 *(u32x4*)(P.q_() + ((size_t)(b * NH + h) * SEQ + i) * DQK + c8) = pack8(acc[ai][bj][m][0] * sc, acc[ai][bj][m][1] * sc); }
.LBB0_488:
	v_and_b32_e32 v144, 0xfef, v131
	s_nop 0
	v_rsq_f32_e32 v133, v163
	s_nop 0
	v_mov_b32_e32 v131, v133
	v_mul_f32_e32 v138, 0x3dd53b94, v131
	v_pk_mul_f32 v[136:137], v[32:33], v[138:139] op_sel_hi:[1,0]
	v_pk_mul_f32 v[134:135], v[30:31], v[138:139] op_sel_hi:[1,0]
	v_pk_mul_f32 v[140:141], v[28:29], v[138:139] op_sel_hi:[1,0]
	v_ashrrev_i32_e32 v131, 31, v130
	v_cvt_pk_bf16_f32 v134, v134, v135
	v_cvt_pk_bf16_f32 v135, v136, v137
	v_cvt_pk_bf16_f32 v137, v140, v141
	v_lshlrev_b64 v[140:141], 12, v[130:131]
	v_pk_mul_f32 v[142:143], v[26:27], v[138:139] op_sel_hi:[1,0]
	v_or_b32_e32 v131, v140, v144
	v_cvt_pk_bf16_f32 v136, v142, v143
	v_mad_u64_u32 v[142:143], s[38:39], v131, s73, v[156:157]
	v_mad_i32_i24 v143, v141, s73, v143
	global_store_dwordx4 v[142:143], v[134:137], off
	v_pk_mul_f32 v[140:141], v[20:21], v[138:139] op_sel_hi:[1,0]
	s_nop 0
	v_pk_mul_f32 v[136:137], v[24:25], v[138:139] op_sel_hi:[1,0]
	v_pk_mul_f32 v[134:135], v[22:23], v[138:139] op_sel_hi:[1,0]
	v_pk_mul_f32 v[138:139], v[18:19], v[138:139] op_sel_hi:[1,0]
	v_cvt_pk_bf16_f32 v134, v134, v135
	v_cvt_pk_bf16_f32 v135, v136, v137
	v_cvt_pk_bf16_f32 v136, v138, v139
	v_add_u32_e32 v138, 1, v130
	v_ashrrev_i32_e32 v139, 31, v138
	v_lshlrev_b64 v[138:139], 12, v[138:139]
	v_or_b32_e32 v131, v138, v144
	v_cvt_pk_bf16_f32 v137, v140, v141
	v_mad_u64_u32 v[140:141], s[38:39], v131, s73, v[156:157]
	v_mad_i32_i24 v141, v139, s73, v141
	global_store_dwordx4 v[140:141], v[134:137], off

; __device__ __forceinline__ u32x4 pack8(const f32x4 a, const f32x4 b) { u32x4 w; w.x = cvt_pk_bf16(a[0], a[1]); w.y = cvt_pk_bf16(a[2], a[3]); w.z = cvt_pk_bf16(b[0], b[1]); w.w = cvt_pk_bf16(b[2], b[3]); return w; }
;     __device__ __forceinline__ void operator()(f32x4 (&acc)[2][2][4][2], const Unit& u, int wr, int wc, int fr, int fq) const {
;     ...
;                     for (int m = 0; m < 4; ++m) { const int row = ROWOF(ai, m);
;                         if (kind == K_QN) { const float sc = rsqrtf(rsv[ai * 4 + m] * (1.0f / 512.0f) + EPS) * QSCALE; const int b = row >> 12, i = row & 4095;
; #pragma unroll
;                             for (int bj = 0; bj < 2; ++bj) { const int h = u.pn * 2 + bj;
;                                 *(u32x4*)(P.q_() + ((size_t)(b * NH + h) * SEQ + i) * DQK + c8) = pack8(acc[ai][bj][m][0] * sc, acc[ai][bj][m][1] * sc); }
.LBB0_493:
	v_and_b32_e32 v142, 0xfff, v131
	s_nop 0
	v_rsq_f32_e32 v132, v162
	s_nop 0
	v_mov_b32_e32 v131, v132
	v_mul_f32_e32 v136, 0x3dd53b94, v131
	v_pk_mul_f32 v[134:135], v[16:17], v[136:137] op_sel_hi:[1,0]
	v_pk_mul_f32 v[132:133], v[14:15], v[136:137] op_sel_hi:[1,0]
	v_pk_mul_f32 v[138:139], v[12:13], v[136:137] op_sel_hi:[1,0]
	v_ashrrev_i32_e32 v131, 31, v130
	v_cvt_pk_bf16_f32 v132, v132, v133
	v_cvt_pk_bf16_f32 v133, v134, v135
	v_cvt_pk_bf16_f32 v135, v138, v139
	v_lshlrev_b64 v[138:139], 12, v[130:131]
	v_pk_mul_f32 v[140:141], v[10:11], v[136:137] op_sel_hi:[1,0]
	v_or_b32_e32 v131, v138, v142
	v_add_u32_e32 v130, 1, v130
	v_cvt_pk_bf16_f32 v134, v140, v141
	v_mad_u64_u32 v[140:141], s[38:39], v131, s73, v[156:157]
	v_ashrrev_i32_e32 v131, 31, v130
	v_mad_i32_i24 v141, v139, s73, v141
	v_lshlrev_b64 v[130:131], 12, v[130:131]
	global_store_dwordx4 v[140:141], v[132:135], off
	v_pk_mul_f32 v[138:139], v[4:5], v[136:137] op_sel_hi:[1,0]
	v_or_b32_e32 v130, v130, v142
	v_pk_mul_f32 v[134:135], v[8:9], v[136:137] op_sel_hi:[1,0]
	v_pk_mul_f32 v[132:133], v[6:7], v[136:137] op_sel_hi:[1,0]
	v_pk_mul_f32 v[136:137], v[2:3], v[136:137] op_sel_hi:[1,0]
	v_cvt_pk_bf16_f32 v132, v132, v133
	v_cvt_pk_bf16_f32 v133, v134, v135
	v_cvt_pk_bf16_f32 v134, v136, v137
	v_mad_u64_u32 v[136:137], s[38:39], v130, s73, v[156:157]
	v_cvt_pk_bf16_f32 v135, v138, v139
	v_mad_i32_i24 v137, v131, s73, v137
	global_store_dwordx4 v[136:137], v[132:135], off

; #define SBAR() __builtin_amdgcn_sched_barrier(0)
; __device__ __forceinline__ unsigned cvt_pk_bf16(float lo, float hi) { const f32x2 v = {lo, hi}; const bf16x2_t b = __builtin_convertvector(v, bf16x2_t); return __builtin_bit_cast(unsigned, b); }
;     __device__ __forceinline__ void operator()(f32x4 (&acc)[2][2][4][2], const Unit& u, int wr, int wc, int fr, int fq) const {
;     ...
;                 for (int ai = 0; ai < 2; ++ai) { f32x4 csv[4][2];
; #pragma unroll
;                     for (int m = 0; m < 4; ++m) { const int pos = NMETA + (ROWOF(ai, m) & 4095); csv[m][0] = *(const f32x4*)(P.cs_() + (size_t)pos * 32 + jp * 4); csv[m][1] = *(const f32x4*)(P.cs_() + (size_t)pos * 32 + jp * 4 + 2); }
;                     SBAR();
; #pragma unroll
;                     for (int m = 0; m < 4; ++m) { const int row = ROWOF(ai, m); const int b = row >> 12, i = row & 4095; const float sc = rsqrtf(rsv[ai * 4 + m] * (1.0f / 512.0f) + EPS) * QSCALE;
;                         const f32x4 cc = {csv[m][0][0], csv[m][0][2], csv[m][1][0], csv[m][1][2]}, sn = {csv[m][0][1], csv[m][0][3], csv[m][1][1], csv[m][1][3]};
; #pragma unroll
;                         for (int bj = 0; bj < 2; ++bj) { const int h = (u.pn - 8) * 4 + bj * 2 + (wc >> 1);
;                             const f32x4 x1 = acc[ai][bj][m][0] * sc, x2 = acc[ai][bj][m][1] * sc; const f32x4 o1 = x1 * cc - x2 * sn, o2 = x2 * cc + x1 * sn;
;                             u32x2 w1, w2; w1.x = cvt_pk_bf16(o1[0], o1[1]); w1.y = cvt_pk_bf16(o1[2], o1[3]); w2.x = cvt_pk_bf16(o2[0], o2[1]); w2.y = cvt_pk_bf16(o2[2], o2[3]);
;                             bf16* d = P.q_() + ((size_t)(b * NH + h) * SEQ + i) * DQK + DNOPE + jp * 4; *(u32x2*)d = w1; *(u32x2*)(d + 32) = w2; } } }
.LBB0_495:
	v_lshlrev_b32_e32 v130, 8, v166
	v_and_b32_e32 v148, 0xfcf00, v130
	v_lshl_add_u64 v[130:131], s[86:87], 0, v[148:149]
	v_lshlrev_b32_e32 v148, 3, v150
	v_lshl_add_u64 v[130:131], v[130:131], 0, v[148:149]
	v_add_co_u32_e32 v134, vcc, 0x111000, v130
	v_lshl_add_u64 v[132:133], v[130:131], 0, s[14:15]
	s_nop 0
	v_addc_co_u32_e32 v135, vcc, 0, v131, vcc
	global_load_dwordx4 v[186:189], v[134:135], off
	global_load_dwordx4 v[190:193], v[132:133], off offset:16
	v_add_co_u32_e32 v134, vcc, 0x112000, v130
	v_lshl_add_u64 v[132:133], v[130:131], 0, s[16:17]
	s_nop 0
	v_addc_co_u32_e32 v135, vcc, 0, v131, vcc
	global_load_dwordx4 v[194:197], v[134:135], off
	global_load_dwordx4 v[198:201], v[132:133], off offset:16
	v_add_co_u32_e32 v134, vcc, 0x113000, v130
	v_lshl_add_u64 v[132:133], v[130:131], 0, s[18:19]
	s_nop 0
	v_addc_co_u32_e32 v135, vcc, 0, v131, vcc
	global_load_dwordx4 v[138:141], v[134:135], off
	global_load_dwordx4 v[142:145], v[132:133], off offset:16
	v_lshl_add_u64 v[134:135], v[130:131], 0, s[20:21]
	v_add_co_u32_e32 v130, vcc, 0x114000, v130
	s_nop 1
	v_addc_co_u32_e32 v131, vcc, 0, v131, vcc
	global_load_dwordx4 v[130:133], v[130:131], off
	s_nop 0
	global_load_dwordx4 v[134:137], v[134:135], off offset:16
	s_ashr_i32 s0, s0, 8
	s_and_b32 s0, s0, -16
	v_rsq_f32_e32 v171, v171
	s_add_i32 s40, s0, s95
	s_lshl_b32 s0, s57, 2
	s_waitcnt vmcnt(0)
	v_mov_b32_e32 v204, v191
	v_mul_f32_e32 v202, 0x3dd53b94, v171
	v_pk_mul_f32 v[122:123], v[122:123], v[202:203] op_sel_hi:[1,0]
	v_pk_mul_f32 v[124:125], v[124:125], v[202:203] op_sel_hi:[1,0]
	v_mov_b32_e32 v205, v193
	v_mov_b32_e32 v208, v187
	v_mov_b32_e32 v209, v189
	v_mov_b32_e32 v187, v188
	v_mov_b32_e32 v191, v192
	s_add_i32 s38, s40, s0
	v_pk_mul_f32 v[128:129], v[128:129], v[202:203] op_sel_hi:[1,0]
	v_pk_mul_f32 v[126:127], v[126:127], v[202:203] op_sel_hi:[1,0]
	v_pk_mul_f32 v[206:207], v[124:125], v[204:205]
	v_pk_mul_f32 v[210:211], v[122:123], v[208:209]
	v_pk_mul_f32 v[124:125], v[124:125], v[190:191]
	v_pk_mul_f32 v[122:123], v[122:123], v[186:187]
	s_ashr_i32 s39, s38, 31
	v_and_b32_e32 v167, 0xfcf, v166
	v_pk_fma_f32 v[122:123], v[126:127], v[208:209], v[122:123]
	v_pk_fma_f32 v[124:125], v[128:129], v[204:205], v[124:125]
	s_lshl_b64 s[56:57], s[38:39], 12
	v_pk_fma_f32 v[188:189], v[126:127], v[186:187], v[210:211] neg_lo:[0,0,1] neg_hi:[0,0,1]
	v_pk_fma_f32 v[192:193], v[128:129], v[190:191], v[206:207] neg_lo:[0,0,1] neg_hi:[0,0,1]
	v_cvt_pk_bf16_f32 v128, v122, v123
	v_cvt_pk_bf16_f32 v129, v124, v125
	v_or_b32_e32 v124, s56, v167
	v_mov_b64_e32 v[122:123], s[86:87]
	v_cvt_pk_bf16_f32 v126, v188, v189
	v_mad_u64_u32 v[188:189], s[38:39], v124, s73, v[122:123]
	v_mad_i32_i24 v189, s57, v183, v189
	v_lshlrev_b32_e32 v124, 1, v150
	v_mov_b32_e32 v125, v149
	v_lshl_add_u64 v[188:189], v[188:189], 0, v[124:125]
	v_cvt_pk_bf16_f32 v127, v192, v193
	v_lshl_add_u64 v[192:193], v[188:189], 0, s[22:23]
	v_add_co_u32_e32 v188, vcc, s74, v188
	s_or_b32 s5, s0, 2
	s_nop 0
	v_addc_co_u32_e32 v189, vcc, 0, v189, vcc
	v_pk_mul_f32 v[114:115], v[114:115], v[202:203] op_sel_hi:[1,0]
	v_pk_mul_f32 v[116:117], v[116:117], v[202:203] op_sel_hi:[1,0]
	s_add_i32 s38, s40, s5
	global_store_dwordx2 v[188:189], v[126:127], off offset:256
	global_store_dwordx2 v[192:193], v[128:129], off offset:64
	v_pk_mul_f32 v[120:121], v[120:121], v[202:203] op_sel_hi:[1,0]
	v_pk_mul_f32 v[118:119], v[118:119], v[202:203] op_sel_hi:[1,0]
	v_pk_mul_f32 v[126:127], v[116:117], v[204:205]
	v_pk_mul_f32 v[128:129], v[114:115], v[208:209]
	v_pk_mul_f32 v[116:117], v[116:117], v[190:191]
	v_pk_mul_f32 v[114:115], v[114:115], v[186:187]
	s_ashr_i32 s39, s38, 31
	v_pk_fma_f32 v[114:115], v[118:119], v[208:209], v[114:115]
	v_pk_fma_f32 v[116:117], v[120:121], v[204:205], v[116:117]
	s_lshl_b64 s[58:59], s[38:39], 12
	v_cvt_pk_bf16_f32 v114, v114, v115
	v_cvt_pk_bf16_f32 v115, v116, v117
	v_or_b32_e32 v116, s58, v167
	v_mad_u64_u32 v[116:117], s[38:39], v116, s73, v[122:123]
	v_mad_i32_i24 v117, s59, v183, v117
	v_lshl_add_u64 v[116:117], v[116:117], 0, v[124:125]
	v_pk_fma_f32 v[126:127], v[120:121], v[190:191], v[126:127] neg_lo:[0,0,1] neg_hi:[0,0,1]
	v_lshl_add_u64 v[120:121], v[116:117], 0, s[22:23]
	v_add_co_u32_e32 v116, vcc, s74, v116
	v_pk_fma_f32 v[128:129], v[118:119], v[186:187], v[128:129] neg_lo:[0,0,1] neg_hi:[0,0,1]
	s_nop 0
	v_addc_co_u32_e32 v117, vcc, 0, v117, vcc
	v_cvt_pk_bf16_f32 v119, v126, v127
	v_cvt_pk_bf16_f32 v118, v128, v129
	global_store_dwordx2 v[116:117], v[118:119], off offset:256
	global_store_dwordx2 v[120:121], v[114:115], off offset:64
	v_rsq_f32_e32 v126, v170
	v_or_b32_e32 v115, 16, v167
	v_mov_b32_e32 v116, v199
	v_mov_b32_e32 v117, v201
	v_mov_b32_e32 v114, v126
	v_mul_f32_e32 v114, 0x3dd53b94, v114
	v_pk_mul_f32 v[106:107], v[106:107], v[114:115] op_sel_hi:[1,0]
	v_pk_mul_f32 v[108:109], v[108:109], v[114:115] op_sel_hi:[1,0]
	v_mov_b32_e32 v120, v195
	v_mov_b32_e32 v121, v197
	v_mov_b32_e32 v195, v196
	v_mov_b32_e32 v199, v200
	v_pk_mul_f32 v[112:113], v[112:113], v[114:115] op_sel_hi:[1,0]
	v_pk_mul_f32 v[110:111], v[110:111], v[114:115] op_sel_hi:[1,0]
	v_pk_mul_f32 v[118:119], v[108:109], v[116:117]
	v_pk_mul_f32 v[126:127], v[106:107], v[120:121]
	v_pk_mul_f32 v[108:109], v[108:109], v[198:199]
	v_pk_mul_f32 v[106:107], v[106:107], v[194:195]
	v_pk_fma_f32 v[108:109], v[112:113], v[116:117], v[108:109]
	v_pk_fma_f32 v[106:107], v[110:111], v[120:121], v[106:107]
	v_pk_fma_f32 v[126:127], v[110:111], v[194:195], v[126:127] neg_lo:[0,0,1] neg_hi:[0,0,1]
	v_cvt_pk_bf16_f32 v106, v106, v107
	v_cvt_pk_bf16_f32 v107, v108, v109
	v_or_b32_e32 v108, s56, v115
; __device__ __forceinline__ unsigned cvt_pk_bf16(float lo, float hi) { const f32x2 v = {lo, hi}; const bf16x2_t b = __builtin_convertvector(v, bf16x2_t); return __builtin_bit_cast(unsigned, b); }
;     __device__ __forceinline__ void operator()(f32x4 (&acc)[2][2][4][2], const Unit& u, int wr, int wc, int fr, int fq) const {
;     ...
;                     for (int m = 0; m < 4; ++m) { const int row = ROWOF(ai, m); const int b = row >> 12, i = row & 4095; const float sc = rsqrtf(rsv[ai * 4 + m] * (1.0f / 512.0f) + EPS) * QSCALE;
;                         const f32x4 cc = {csv[m][0][0], csv[m][0][2], csv[m][1][0], csv[m][1][2]}, sn = {csv[m][0][1], csv[m][0][3], csv[m][1][1], csv[m][1][3]};
; #pragma unroll
;                         for (int bj = 0; bj < 2; ++bj) { const int h = (u.pn - 8) * 4 + bj * 2 + (wc >> 1);
;                             const f32x4 x1 = acc[ai][bj][m][0] * sc, x2 = acc[ai][bj][m][1] * sc; const f32x4 o1 = x1 * cc - x2 * sn, o2 = x2 * cc + x1 * sn;
;                             u32x2 w1, w2; w1.x = cvt_pk_bf16(o1[0], o1[1]); w1.y = cvt_pk_bf16(o1[2], o1[3]); w2.x = cvt_pk_bf16(o2[0], o2[1]); w2.y = cvt_pk_bf16(o2[2], o2[3]);
;                             bf16* d = P.q_() + ((size_t)(b * NH + h) * SEQ + i) * DQK + DNOPE + jp * 4; *(u32x2*)d = w1; *(u32x2*)(d + 32) = w2; } } }
	v_mad_u64_u32 v[108:109], s[38:39], v108, s73, v[122:123]
	v_mad_i32_i24 v109, s57, v183, v109
	v_lshl_add_u64 v[108:109], v[108:109], 0, v[124:125]
	v_pk_fma_f32 v[118:119], v[112:113], v[198:199], v[118:119] neg_lo:[0,0,1] neg_hi:[0,0,1]
	v_lshl_add_u64 v[112:113], v[108:109], 0, s[22:23]
	v_add_co_u32_e32 v108, vcc, s74, v108
	v_cvt_pk_bf16_f32 v110, v126, v127
	v_cvt_pk_bf16_f32 v111, v118, v119
	v_addc_co_u32_e32 v109, vcc, 0, v109, vcc
	v_pk_mul_f32 v[98:99], v[98:99], v[114:115] op_sel_hi:[1,0]
	v_pk_mul_f32 v[100:101], v[100:101], v[114:115] op_sel_hi:[1,0]
	global_store_dwordx2 v[108:109], v[110:111], off offset:256
	global_store_dwordx2 v[112:113], v[106:107], off offset:64
	v_pk_mul_f32 v[104:105], v[104:105], v[114:115] op_sel_hi:[1,0]
	v_pk_mul_f32 v[102:103], v[102:103], v[114:115] op_sel_hi:[1,0]
	v_pk_mul_f32 v[106:107], v[100:101], v[116:117]
	v_pk_mul_f32 v[108:109], v[98:99], v[120:121]
	v_pk_mul_f32 v[100:101], v[100:101], v[198:199]
	v_pk_mul_f32 v[98:99], v[98:99], v[194:195]
	v_pk_fma_f32 v[100:101], v[104:105], v[116:117], v[100:101]
	v_pk_fma_f32 v[98:99], v[102:103], v[120:121], v[98:99]
	v_pk_fma_f32 v[106:107], v[104:105], v[198:199], v[106:107] neg_lo:[0,0,1] neg_hi:[0,0,1]
	v_cvt_pk_bf16_f32 v98, v98, v99
	v_cvt_pk_bf16_f32 v99, v100, v101
	v_or_b32_e32 v100, s58, v115
	v_mad_u64_u32 v[100:101], s[38:39], v100, s73, v[122:123]
	v_mad_i32_i24 v101, s59, v183, v101
	v_lshl_add_u64 v[100:101], v[100:101], 0, v[124:125]
	v_lshl_add_u64 v[104:105], v[100:101], 0, s[22:23]
	v_add_co_u32_e32 v100, vcc, s74, v100
	v_pk_fma_f32 v[108:109], v[102:103], v[194:195], v[108:109] neg_lo:[0,0,1] neg_hi:[0,0,1]
	s_nop 0
	v_addc_co_u32_e32 v101, vcc, 0, v101, vcc
	v_cvt_pk_bf16_f32 v103, v106, v107
	v_cvt_pk_bf16_f32 v102, v108, v109
	global_store_dwordx2 v[100:101], v[102:103], off offset:256
	global_store_dwordx2 v[104:105], v[98:99], off offset:64
	v_rsq_f32_e32 v106, v169
	v_or_b32_e32 v99, 32, v167
	v_mov_b32_e32 v100, v143
	v_mov_b32_e32 v101, v145
	v_mov_b32_e32 v98, v106
	v_mul_f32_e32 v98, 0x3dd53b94, v98
	v_pk_mul_f32 v[90:91], v[90:91], v[98:99] op_sel_hi:[1,0]
	v_pk_mul_f32 v[92:93], v[92:93], v[98:99] op_sel_hi:[1,0]
	v_mov_b32_e32 v104, v139
	v_mov_b32_e32 v105, v141
	v_mov_b32_e32 v139, v140
	v_mov_b32_e32 v143, v144
	v_pk_mul_f32 v[96:97], v[96:97], v[98:99] op_sel_hi:[1,0]
	v_pk_mul_f32 v[94:95], v[94:95], v[98:99] op_sel_hi:[1,0]
	v_pk_mul_f32 v[102:103], v[92:93], v[100:101]
	v_pk_mul_f32 v[106:107], v[90:91], v[104:105]
	v_pk_mul_f32 v[92:93], v[92:93], v[142:143]
	v_pk_mul_f32 v[90:91], v[90:91], v[138:139]
	v_pk_fma_f32 v[92:93], v[96:97], v[100:101], v[92:93]
	v_pk_fma_f32 v[90:91], v[94:95], v[104:105], v[90:91]
	v_pk_fma_f32 v[106:107], v[94:95], v[138:139], v[106:107] neg_lo:[0,0,1] neg_hi:[0,0,1]
	v_cvt_pk_bf16_f32 v90, v90, v91
	v_cvt_pk_bf16_f32 v91, v92, v93
	v_or_b32_e32 v92, s56, v99
	v_mad_u64_u32 v[92:93], s[38:39], v92, s73, v[122:123]
	v_mad_i32_i24 v93, s57, v183, v93
	v_lshl_add_u64 v[92:93], v[92:93], 0, v[124:125]
	v_pk_fma_f32 v[102:103], v[96:97], v[142:143], v[102:103] neg_lo:[0,0,1] neg_hi:[0,0,1]
	v_lshl_add_u64 v[96:97], v[92:93], 0, s[22:23]
	v_add_co_u32_e32 v92, vcc, s74, v92
	v_cvt_pk_bf16_f32 v94, v106, v107
	v_cvt_pk_bf16_f32 v95, v102, v103
	v_addc_co_u32_e32 v93, vcc, 0, v93, vcc
	v_pk_mul_f32 v[82:83], v[82:83], v[98:99] op_sel_hi:[1,0]
	v_pk_mul_f32 v[84:85], v[84:85], v[98:99] op_sel_hi:[1,0]
	global_store_dwordx2 v[92:93], v[94:95], off offset:256
	global_store_dwordx2 v[96:97], v[90:91], off offset:64
	v_pk_mul_f32 v[88:89], v[88:89], v[98:99] op_sel_hi:[1,0]
	v_pk_mul_f32 v[86:87], v[86:87], v[98:99] op_sel_hi:[1,0]
	v_pk_mul_f32 v[90:91], v[84:85], v[100:101]
	v_pk_mul_f32 v[92:93], v[82:83], v[104:105]
	v_pk_mul_f32 v[84:85], v[84:85], v[142:143]
	v_pk_mul_f32 v[82:83], v[82:83], v[138:139]
	v_pk_fma_f32 v[84:85], v[88:89], v[100:101], v[84:85]
	v_pk_fma_f32 v[82:83], v[86:87], v[104:105], v[82:83]
	v_pk_fma_f32 v[90:91], v[88:89], v[142:143], v[90:91] neg_lo:[0,0,1] neg_hi:[0,0,1]
	v_cvt_pk_bf16_f32 v82, v82, v83
	v_cvt_pk_bf16_f32 v83, v84, v85
	v_or_b32_e32 v84, s58, v99
	v_mad_u64_u32 v[84:85], s[38:39], v84, s73, v[122:123]
	v_mad_i32_i24 v85, s59, v183, v85
	v_lshl_add_u64 v[84:85], v[84:85], 0, v[124:125]
	v_lshl_add_u64 v[88:89], v[84:85], 0, s[22:23]
	v_add_co_u32_e32 v84, vcc, s74, v84
	v_pk_fma_f32 v[92:93], v[86:87], v[138:139], v[92:93] neg_lo:[0,0,1] neg_hi:[0,0,1]
	s_nop 0
	v_addc_co_u32_e32 v85, vcc, 0, v85, vcc
	v_cvt_pk_bf16_f32 v87, v90, v91
	v_cvt_pk_bf16_f32 v86, v92, v93
	global_store_dwordx2 v[84:85], v[86:87], off offset:256
	global_store_dwordx2 v[88:89], v[82:83], off offset:64
	v_rsq_f32_e32 v90, v168
	v_or_b32_e32 v83, 48, v167
	v_mov_b32_e32 v84, v135
	v_mov_b32_e32 v85, v137
	v_mov_b32_e32 v82, v90
	v_mul_f32_e32 v82, 0x3dd53b94, v82
	v_pk_mul_f32 v[74:75], v[74:75], v[82:83] op_sel_hi:[1,0]
	v_pk_mul_f32 v[76:77], v[76:77], v[82:83] op_sel_hi:[1,0]
	v_mov_b32_e32 v88, v131
	v_mov_b32_e32 v89, v133
	v_mov_b32_e32 v131, v132
	v_mov_b32_e32 v135, v136
	v_pk_mul_f32 v[80:81], v[80:81], v[82:83] op_sel_hi:[1,0]
	v_pk_mul_f32 v[78:79], v[78:79], v[82:83] op_sel_hi:[1,0]
	v_pk_mul_f32 v[86:87], v[76:77], v[84:85]
	v_pk_mul_f32 v[90:91], v[74:75], v[88:89]
	v_pk_mul_f32 v[76:77], v[76:77], v[134:135]
	v_pk_mul_f32 v[74:75], v[74:75], v[130:131]
	v_pk_fma_f32 v[76:77], v[80:81], v[84:85], v[76:77]
	v_pk_fma_f32 v[74:75], v[78:79], v[88:89], v[74:75]
	v_pk_fma_f32 v[90:91], v[78:79], v[130:131], v[90:91] neg_lo:[0,0,1] neg_hi:[0,0,1]
	v_cvt_pk_bf16_f32 v74, v74, v75
	v_cvt_pk_bf16_f32 v75, v76, v77
	v_or_b32_e32 v76, s56, v83
; #define SBAR() __builtin_amdgcn_sched_barrier(0)
; __device__ __forceinline__ unsigned cvt_pk_bf16(float lo, float hi) { const f32x2 v = {lo, hi}; const bf16x2_t b = __builtin_convertvector(v, bf16x2_t); return __builtin_bit_cast(unsigned, b); }
;     __device__ __forceinline__ void operator()(f32x4 (&acc)[2][2][4][2], const Unit& u, int wr, int wc, int fr, int fq) const {
;     ...
;                 for (int ai = 0; ai < 2; ++ai) { f32x4 csv[4][2];
; #pragma unroll
;                     for (int m = 0; m < 4; ++m) { const int pos = NMETA + (ROWOF(ai, m) & 4095); csv[m][0] = *(const f32x4*)(P.cs_() + (size_t)pos * 32 + jp * 4); csv[m][1] = *(const f32x4*)(P.cs_() + (size_t)pos * 32 + jp * 4 + 2); }
;                     SBAR();
; #pragma unroll
;                     for (int m = 0; m < 4; ++m) { const int row = ROWOF(ai, m); const int b = row >> 12, i = row & 4095; const float sc = rsqrtf(rsv[ai * 4 + m] * (1.0f / 512.0f) + EPS) * QSCALE;
;                         const f32x4 cc = {csv[m][0][0], csv[m][0][2], csv[m][1][0], csv[m][1][2]}, sn = {csv[m][0][1], csv[m][0][3], csv[m][1][1], csv[m][1][3]};
; #pragma unroll
;                         for (int bj = 0; bj < 2; ++bj) { const int h = (u.pn - 8) * 4 + bj * 2 + (wc >> 1);
;                             const f32x4 x1 = acc[ai][bj][m][0] * sc, x2 = acc[ai][bj][m][1] * sc; const f32x4 o1 = x1 * cc - x2 * sn, o2 = x2 * cc + x1 * sn;
;                             u32x2 w1, w2; w1.x = cvt_pk_bf16(o1[0], o1[1]); w1.y = cvt_pk_bf16(o1[2], o1[3]); w2.x = cvt_pk_bf16(o2[0], o2[1]); w2.y = cvt_pk_bf16(o2[2], o2[3]);
;                             bf16* d = P.q_() + ((size_t)(b * NH + h) * SEQ + i) * DQK + DNOPE + jp * 4; *(u32x2*)d = w1; *(u32x2*)(d + 32) = w2; } } }
	v_mad_u64_u32 v[76:77], s[38:39], v76, s73, v[122:123]
	v_mad_i32_i24 v77, s57, v183, v77
	v_lshl_add_u64 v[76:77], v[76:77], 0, v[124:125]
	v_pk_fma_f32 v[86:87], v[80:81], v[134:135], v[86:87] neg_lo:[0,0,1] neg_hi:[0,0,1]
	v_lshl_add_u64 v[80:81], v[76:77], 0, s[22:23]
	v_add_co_u32_e32 v76, vcc, s74, v76
	v_cvt_pk_bf16_f32 v78, v90, v91
	v_cvt_pk_bf16_f32 v79, v86, v87
	v_addc_co_u32_e32 v77, vcc, 0, v77, vcc
	v_pk_mul_f32 v[66:67], v[66:67], v[82:83] op_sel_hi:[1,0]
	v_pk_mul_f32 v[68:69], v[68:69], v[82:83] op_sel_hi:[1,0]
	global_store_dwordx2 v[76:77], v[78:79], off offset:256
	global_store_dwordx2 v[80:81], v[74:75], off offset:64
	v_pk_mul_f32 v[72:73], v[72:73], v[82:83] op_sel_hi:[1,0]
	v_pk_mul_f32 v[70:71], v[70:71], v[82:83] op_sel_hi:[1,0]
	v_pk_mul_f32 v[74:75], v[68:69], v[84:85]
	v_pk_mul_f32 v[76:77], v[66:67], v[88:89]
	v_pk_mul_f32 v[68:69], v[68:69], v[134:135]
	v_pk_mul_f32 v[66:67], v[66:67], v[130:131]
	v_pk_fma_f32 v[68:69], v[72:73], v[84:85], v[68:69]
	v_pk_fma_f32 v[66:67], v[70:71], v[88:89], v[66:67]
	v_pk_fma_f32 v[76:77], v[70:71], v[130:131], v[76:77] neg_lo:[0,0,1] neg_hi:[0,0,1]
	v_cvt_pk_bf16_f32 v66, v66, v67
	v_cvt_pk_bf16_f32 v67, v68, v69
	v_or_b32_e32 v68, s58, v83
	v_mad_u64_u32 v[68:69], s[38:39], v68, s73, v[122:123]
	v_mad_i32_i24 v69, s59, v183, v69
	v_lshl_add_u64 v[68:69], v[68:69], 0, v[124:125]
	v_pk_fma_f32 v[74:75], v[72:73], v[134:135], v[74:75] neg_lo:[0,0,1] neg_hi:[0,0,1]
	v_lshl_add_u64 v[72:73], v[68:69], 0, s[22:23]
	v_add_co_u32_e32 v68, vcc, s74, v68
	v_cvt_pk_bf16_f32 v70, v76, v77
	v_cvt_pk_bf16_f32 v71, v74, v75
	v_addc_co_u32_e32 v69, vcc, 0, v69, vcc
	global_store_dwordx2 v[68:69], v[70:71], off offset:256
	global_store_dwordx2 v[72:73], v[66:67], off offset:64
	v_lshl_add_u32 v66, v166, 5, v184
	v_and_b32_e32 v66, 0x1f9e0, v66
	v_lshlrev_b32_e32 v66, 3, v66
	v_mov_b32_e32 v67, v149
	v_lshl_add_u64 v[66:67], s[86:87], 0, v[66:67]
	v_lshl_add_u64 v[66:67], v[66:67], 0, v[148:149]
	s_mov_b32 s38, 0x112000
	v_add_co_u32_e32 v70, vcc, s38, v66
	v_lshl_add_u64 v[68:69], v[66:67], 0, s[14:15]
	s_nop 0
	v_addc_co_u32_e32 v71, vcc, 0, v67, vcc
	s_mov_b32 s38, 0x114000
	v_lshl_add_u64 v[72:73], v[66:67], 0, s[16:17]
	global_load_dwordx4 v[82:85], v[70:71], off offset:-4096
	global_load_dwordx4 v[86:89], v[70:71], off
	global_load_dwordx4 v[90:93], v[68:69], off offset:16
	global_load_dwordx4 v[94:97], v[72:73], off offset:16
	v_add_co_u32_e32 v68, vcc, s38, v66
	v_lshl_add_u64 v[70:71], v[66:67], 0, s[18:19]
	s_nop 0
	v_addc_co_u32_e32 v69, vcc, 0, v67, vcc
	v_lshl_add_u64 v[72:73], v[66:67], 0, s[20:21]
	global_load_dwordx4 v[74:77], v[68:69], off offset:-4096
	s_nop 0
	global_load_dwordx4 v[66:69], v[68:69], off
	s_nop 0
	global_load_dwordx4 v[78:81], v[70:71], off offset:16
	s_nop 0
	global_load_dwordx4 v[70:73], v[72:73], off offset:16
	v_add_u32_e32 v98, 0x80, v166
	v_and_b32_e32 v99, 0xfcf, v98
	v_rsq_f32_e32 v100, v165
	v_ashrrev_i32_e32 v98, 8, v98
	v_and_b32_e32 v98, -16, v98
	v_add_u32_e32 v108, s95, v98
	v_mov_b32_e32 v98, v100
	v_mul_f32_e32 v98, 0x3dd53b94, v98
	v_pk_mul_f32 v[58:59], v[58:59], v[98:99] op_sel_hi:[1,0]
	s_waitcnt vmcnt(7)
	v_mov_b32_e32 v104, v83
	v_mov_b32_e32 v105, v85
	v_mov_b32_e32 v83, v84
	v_pk_mul_f32 v[62:63], v[62:63], v[98:99] op_sel_hi:[1,0]
	v_pk_mul_f32 v[60:61], v[60:61], v[98:99] op_sel_hi:[1,0]
	s_waitcnt vmcnt(5)
	v_mov_b32_e32 v100, v91
	v_mov_b32_e32 v101, v93
	v_pk_mul_f32 v[106:107], v[58:59], v[104:105]
	v_mov_b32_e32 v91, v92
	v_pk_mul_f32 v[58:59], v[58:59], v[82:83]
	v_pk_mul_f32 v[64:65], v[64:65], v[98:99] op_sel_hi:[1,0]
	v_pk_mul_f32 v[102:103], v[60:61], v[100:101]
	v_pk_mul_f32 v[60:61], v[60:61], v[90:91]
	v_pk_fma_f32 v[58:59], v[62:63], v[104:105], v[58:59]
	v_pk_fma_f32 v[92:93], v[64:65], v[90:91], v[102:103] neg_lo:[0,0,1] neg_hi:[0,0,1]
	v_pk_fma_f32 v[60:61], v[64:65], v[100:101], v[60:61]
	v_cvt_pk_bf16_f32 v64, v58, v59
	v_add_u32_e32 v58, s0, v108
	v_ashrrev_i32_e32 v59, 31, v58
	v_lshlrev_b64 v[58:59], 12, v[58:59]
	v_cvt_pk_bf16_f32 v65, v60, v61
	v_or_b32_e32 v60, v58, v99
	v_mad_u64_u32 v[60:61], s[38:39], v60, s73, v[122:123]
	v_mad_i32_i24 v61, v59, s73, v61
	v_pk_fma_f32 v[84:85], v[62:63], v[82:83], v[106:107] neg_lo:[0,0,1] neg_hi:[0,0,1]
	v_lshl_add_u64 v[60:61], v[60:61], 0, v[124:125]
	v_cvt_pk_bf16_f32 v62, v84, v85
	v_lshl_add_u64 v[84:85], v[60:61], 0, s[22:23]
	v_add_co_u32_e32 v60, vcc, s74, v60
	v_cvt_pk_bf16_f32 v63, v92, v93
	s_nop 0
	v_addc_co_u32_e32 v61, vcc, 0, v61, vcc
	v_pk_mul_f32 v[50:51], v[50:51], v[98:99] op_sel_hi:[1,0]
	global_store_dwordx2 v[60:61], v[62:63], off offset:256
	global_store_dwordx2 v[84:85], v[64:65], off offset:64
	v_pk_mul_f32 v[54:55], v[54:55], v[98:99] op_sel_hi:[1,0]
	v_pk_mul_f32 v[52:53], v[52:53], v[98:99] op_sel_hi:[1,0]
	v_pk_mul_f32 v[62:63], v[50:51], v[104:105]
	v_pk_mul_f32 v[50:51], v[50:51], v[82:83]
	v_pk_mul_f32 v[56:57], v[56:57], v[98:99] op_sel_hi:[1,0]
	v_pk_mul_f32 v[60:61], v[52:53], v[100:101]
	v_pk_mul_f32 v[52:53], v[52:53], v[90:91]
	v_pk_fma_f32 v[50:51], v[54:55], v[104:105], v[50:51]
	v_pk_fma_f32 v[60:61], v[56:57], v[90:91], v[60:61] neg_lo:[0,0,1] neg_hi:[0,0,1]
	v_pk_fma_f32 v[52:53], v[56:57], v[100:101], v[52:53]
	v_cvt_pk_bf16_f32 v56, v50, v51
	v_add_u32_e32 v50, s5, v108
	v_ashrrev_i32_e32 v51, 31, v50
	v_lshlrev_b64 v[50:51], 12, v[50:51]
	v_cvt_pk_bf16_f32 v57, v52, v53
	v_or_b32_e32 v52, v50, v99
	v_mad_u64_u32 v[52:53], s[38:39], v52, s73, v[122:123]
	v_mad_i32_i24 v53, v51, s73, v53
	v_lshl_add_u64 v[52:53], v[52:53], 0, v[124:125]
	v_pk_fma_f32 v[62:63], v[54:55], v[82:83], v[62:63] neg_lo:[0,0,1] neg_hi:[0,0,1]
	v_cvt_pk_bf16_f32 v55, v60, v61
	v_lshl_add_u64 v[60:61], v[52:53], 0, s[22:23]
	v_add_co_u32_e32 v52, vcc, s74, v52
	v_cvt_pk_bf16_f32 v54, v62, v63
	s_nop 0
	v_addc_co_u32_e32 v53, vcc, 0, v53, vcc
	global_store_dwordx2 v[52:53], v[54:55], off offset:256
	global_store_dwordx2 v[60:61], v[56:57], off offset:64
	v_rsq_f32_e32 v62, v164
	v_or_b32_e32 v53, 16, v99
	s_waitcnt vmcnt(8)
; __device__ __forceinline__ unsigned cvt_pk_bf16(float lo, float hi) { const f32x2 v = {lo, hi}; const bf16x2_t b = __builtin_convertvector(v, bf16x2_t); return __builtin_bit_cast(unsigned, b); }
;     __device__ __forceinline__ void operator()(f32x4 (&acc)[2][2][4][2], const Unit& u, int wr, int wc, int fr, int fq) const {
;     ...
;                     for (int m = 0; m < 4; ++m) { const int row = ROWOF(ai, m); const int b = row >> 12, i = row & 4095; const float sc = rsqrtf(rsv[ai * 4 + m] * (1.0f / 512.0f) + EPS) * QSCALE;
;                         const f32x4 cc = {csv[m][0][0], csv[m][0][2], csv[m][1][0], csv[m][1][2]}, sn = {csv[m][0][1], csv[m][0][3], csv[m][1][1], csv[m][1][3]};
; #pragma unroll
;                         for (int bj = 0; bj < 2; ++bj) { const int h = (u.pn - 8) * 4 + bj * 2 + (wc >> 1);
;                             const f32x4 x1 = acc[ai][bj][m][0] * sc, x2 = acc[ai][bj][m][1] * sc; const f32x4 o1 = x1 * cc - x2 * sn, o2 = x2 * cc + x1 * sn;
;                             u32x2 w1, w2; w1.x = cvt_pk_bf16(o1[0], o1[1]); w1.y = cvt_pk_bf16(o1[2], o1[3]); w2.x = cvt_pk_bf16(o2[0], o2[1]); w2.y = cvt_pk_bf16(o2[2], o2[3]);
;                             bf16* d = P.q_() + ((size_t)(b * NH + h) * SEQ + i) * DQK + DNOPE + jp * 4; *(u32x2*)d = w1; *(u32x2*)(d + 32) = w2; } } }
	v_mov_b32_e32 v54, v95
	v_mov_b32_e32 v55, v97
	v_mov_b32_e32 v52, v62
	v_mul_f32_e32 v52, 0x3dd53b94, v52
	v_pk_mul_f32 v[42:43], v[42:43], v[52:53] op_sel_hi:[1,0]
	v_pk_mul_f32 v[44:45], v[44:45], v[52:53] op_sel_hi:[1,0]
	v_mov_b32_e32 v60, v87
	v_mov_b32_e32 v61, v89
	v_mov_b32_e32 v87, v88
	v_mov_b32_e32 v95, v96
	v_pk_mul_f32 v[48:49], v[48:49], v[52:53] op_sel_hi:[1,0]
	v_pk_mul_f32 v[46:47], v[46:47], v[52:53] op_sel_hi:[1,0]
	v_pk_mul_f32 v[56:57], v[44:45], v[54:55]
	v_pk_mul_f32 v[62:63], v[42:43], v[60:61]
	v_pk_mul_f32 v[44:45], v[44:45], v[94:95]
	v_pk_mul_f32 v[42:43], v[42:43], v[86:87]
	v_pk_fma_f32 v[44:45], v[48:49], v[54:55], v[44:45]
	v_pk_fma_f32 v[42:43], v[46:47], v[60:61], v[42:43]
	v_pk_fma_f32 v[62:63], v[46:47], v[86:87], v[62:63] neg_lo:[0,0,1] neg_hi:[0,0,1]
	v_cvt_pk_bf16_f32 v42, v42, v43
	v_cvt_pk_bf16_f32 v43, v44, v45
	v_or_b32_e32 v44, v58, v53
	v_mad_u64_u32 v[44:45], s[38:39], v44, s73, v[122:123]
	v_mad_i32_i24 v45, v59, s73, v45
	v_lshl_add_u64 v[44:45], v[44:45], 0, v[124:125]
	v_pk_fma_f32 v[56:57], v[48:49], v[94:95], v[56:57] neg_lo:[0,0,1] neg_hi:[0,0,1]
	v_lshl_add_u64 v[48:49], v[44:45], 0, s[22:23]
	v_add_co_u32_e32 v44, vcc, s74, v44
	v_cvt_pk_bf16_f32 v46, v62, v63
	v_cvt_pk_bf16_f32 v47, v56, v57
	v_addc_co_u32_e32 v45, vcc, 0, v45, vcc
	v_pk_mul_f32 v[34:35], v[34:35], v[52:53] op_sel_hi:[1,0]
	v_pk_mul_f32 v[36:37], v[36:37], v[52:53] op_sel_hi:[1,0]
	global_store_dwordx2 v[44:45], v[46:47], off offset:256
	global_store_dwordx2 v[48:49], v[42:43], off offset:64
	v_pk_mul_f32 v[40:41], v[40:41], v[52:53] op_sel_hi:[1,0]
	v_pk_mul_f32 v[38:39], v[38:39], v[52:53] op_sel_hi:[1,0]
	v_pk_mul_f32 v[42:43], v[36:37], v[54:55]
	v_pk_mul_f32 v[44:45], v[34:35], v[60:61]
	v_pk_mul_f32 v[36:37], v[36:37], v[94:95]
	v_pk_mul_f32 v[34:35], v[34:35], v[86:87]
	v_pk_fma_f32 v[36:37], v[40:41], v[54:55], v[36:37]
	v_pk_fma_f32 v[34:35], v[38:39], v[60:61], v[34:35]
	v_pk_fma_f32 v[42:43], v[40:41], v[94:95], v[42:43] neg_lo:[0,0,1] neg_hi:[0,0,1]
	v_cvt_pk_bf16_f32 v34, v34, v35
	v_cvt_pk_bf16_f32 v35, v36, v37
	v_or_b32_e32 v36, v50, v53
	v_mad_u64_u32 v[36:37], s[38:39], v36, s73, v[122:123]
	v_mad_i32_i24 v37, v51, s73, v37
	v_lshl_add_u64 v[36:37], v[36:37], 0, v[124:125]
	v_lshl_add_u64 v[40:41], v[36:37], 0, s[22:23]
	v_add_co_u32_e32 v36, vcc, s74, v36
	v_pk_fma_f32 v[44:45], v[38:39], v[86:87], v[44:45] neg_lo:[0,0,1] neg_hi:[0,0,1]
	s_nop 0
	v_addc_co_u32_e32 v37, vcc, 0, v37, vcc
	v_cvt_pk_bf16_f32 v39, v42, v43
	v_cvt_pk_bf16_f32 v38, v44, v45
	global_store_dwordx2 v[36:37], v[38:39], off offset:256
	global_store_dwordx2 v[40:41], v[34:35], off offset:64
	v_rsq_f32_e32 v42, v163
	v_or_b32_e32 v35, 32, v99
	s_waitcnt vmcnt(9)
; __device__ __forceinline__ unsigned cvt_pk_bf16(float lo, float hi) { const f32x2 v = {lo, hi}; const bf16x2_t b = __builtin_convertvector(v, bf16x2_t); return __builtin_bit_cast(unsigned, b); }
;     __device__ __forceinline__ void operator()(f32x4 (&acc)[2][2][4][2], const Unit& u, int wr, int wc, int fr, int fq) const {
;     ...
;                     for (int m = 0; m < 4; ++m) { const int row = ROWOF(ai, m); const int b = row >> 12, i = row & 4095; const float sc = rsqrtf(rsv[ai * 4 + m] * (1.0f / 512.0f) + EPS) * QSCALE;
;                         const f32x4 cc = {csv[m][0][0], csv[m][0][2], csv[m][1][0], csv[m][1][2]}, sn = {csv[m][0][1], csv[m][0][3], csv[m][1][1], csv[m][1][3]};
; #pragma unroll
;                         for (int bj = 0; bj < 2; ++bj) { const int h = (u.pn - 8) * 4 + bj * 2 + (wc >> 1);
;                             const f32x4 x1 = acc[ai][bj][m][0] * sc, x2 = acc[ai][bj][m][1] * sc; const f32x4 o1 = x1 * cc - x2 * sn, o2 = x2 * cc + x1 * sn;
;                             u32x2 w1, w2; w1.x = cvt_pk_bf16(o1[0], o1[1]); w1.y = cvt_pk_bf16(o1[2], o1[3]); w2.x = cvt_pk_bf16(o2[0], o2[1]); w2.y = cvt_pk_bf16(o2[2], o2[3]);
;                             bf16* d = P.q_() + ((size_t)(b * NH + h) * SEQ + i) * DQK + DNOPE + jp * 4; *(u32x2*)d = w1; *(u32x2*)(d + 32) = w2; } } }
	v_mov_b32_e32 v36, v79
	v_mov_b32_e32 v37, v81
	v_mov_b32_e32 v34, v42
	v_mul_f32_e32 v34, 0x3dd53b94, v34
	v_pk_mul_f32 v[26:27], v[26:27], v[34:35] op_sel_hi:[1,0]
	v_pk_mul_f32 v[28:29], v[28:29], v[34:35] op_sel_hi:[1,0]
	v_mov_b32_e32 v40, v75
	v_mov_b32_e32 v41, v77
	v_mov_b32_e32 v75, v76
	v_mov_b32_e32 v79, v80
	v_pk_mul_f32 v[32:33], v[32:33], v[34:35] op_sel_hi:[1,0]
	v_pk_mul_f32 v[30:31], v[30:31], v[34:35] op_sel_hi:[1,0]
	v_pk_mul_f32 v[38:39], v[28:29], v[36:37]
	v_pk_mul_f32 v[42:43], v[26:27], v[40:41]
	v_pk_mul_f32 v[28:29], v[28:29], v[78:79]
	v_pk_mul_f32 v[26:27], v[26:27], v[74:75]
	v_pk_fma_f32 v[28:29], v[32:33], v[36:37], v[28:29]
	v_pk_fma_f32 v[26:27], v[30:31], v[40:41], v[26:27]
	v_pk_fma_f32 v[42:43], v[30:31], v[74:75], v[42:43] neg_lo:[0,0,1] neg_hi:[0,0,1]
	v_cvt_pk_bf16_f32 v26, v26, v27
	v_cvt_pk_bf16_f32 v27, v28, v29
	v_or_b32_e32 v28, v58, v35
	v_mad_u64_u32 v[28:29], s[38:39], v28, s73, v[122:123]
	v_mad_i32_i24 v29, v59, s73, v29
	v_lshl_add_u64 v[28:29], v[28:29], 0, v[124:125]
	v_pk_fma_f32 v[38:39], v[32:33], v[78:79], v[38:39] neg_lo:[0,0,1] neg_hi:[0,0,1]
	v_lshl_add_u64 v[32:33], v[28:29], 0, s[22:23]
	v_add_co_u32_e32 v28, vcc, s74, v28
	v_cvt_pk_bf16_f32 v30, v42, v43
	v_cvt_pk_bf16_f32 v31, v38, v39
	v_addc_co_u32_e32 v29, vcc, 0, v29, vcc
	v_pk_mul_f32 v[18:19], v[18:19], v[34:35] op_sel_hi:[1,0]
	v_pk_mul_f32 v[20:21], v[20:21], v[34:35] op_sel_hi:[1,0]
	global_store_dwordx2 v[28:29], v[30:31], off offset:256
	global_store_dwordx2 v[32:33], v[26:27], off offset:64
	v_pk_mul_f32 v[24:25], v[24:25], v[34:35] op_sel_hi:[1,0]
	v_pk_mul_f32 v[22:23], v[22:23], v[34:35] op_sel_hi:[1,0]
	v_pk_mul_f32 v[26:27], v[20:21], v[36:37]
	v_pk_mul_f32 v[28:29], v[18:19], v[40:41]
	v_pk_mul_f32 v[20:21], v[20:21], v[78:79]
	v_pk_mul_f32 v[18:19], v[18:19], v[74:75]
	v_pk_fma_f32 v[20:21], v[24:25], v[36:37], v[20:21]
	v_pk_fma_f32 v[18:19], v[22:23], v[40:41], v[18:19]
	v_pk_fma_f32 v[26:27], v[24:25], v[78:79], v[26:27] neg_lo:[0,0,1] neg_hi:[0,0,1]
	v_cvt_pk_bf16_f32 v18, v18, v19
	v_cvt_pk_bf16_f32 v19, v20, v21
	v_or_b32_e32 v20, v50, v35
	v_mad_u64_u32 v[20:21], s[38:39], v20, s73, v[122:123]
	v_mad_i32_i24 v21, v51, s73, v21
	v_lshl_add_u64 v[20:21], v[20:21], 0, v[124:125]
	v_lshl_add_u64 v[24:25], v[20:21], 0, s[22:23]
	v_add_co_u32_e32 v20, vcc, s74, v20
	v_pk_fma_f32 v[28:29], v[22:23], v[74:75], v[28:29] neg_lo:[0,0,1] neg_hi:[0,0,1]
	s_nop 0
	v_addc_co_u32_e32 v21, vcc, 0, v21, vcc
	v_cvt_pk_bf16_f32 v23, v26, v27
	v_cvt_pk_bf16_f32 v22, v28, v29
	global_store_dwordx2 v[20:21], v[22:23], off offset:256
	global_store_dwordx2 v[24:25], v[18:19], off offset:64
	v_rsq_f32_e32 v26, v162
	v_or_b32_e32 v19, 48, v99
	s_waitcnt vmcnt(12)
	v_mov_b32_e32 v20, v71
	v_mov_b32_e32 v21, v73
	v_mov_b32_e32 v18, v26
	v_mul_f32_e32 v18, 0x3dd53b94, v18
	v_pk_mul_f32 v[10:11], v[10:11], v[18:19] op_sel_hi:[1,0]
	v_pk_mul_f32 v[12:13], v[12:13], v[18:19] op_sel_hi:[1,0]
	v_mov_b32_e32 v24, v67
	v_mov_b32_e32 v25, v69
	v_mov_b32_e32 v67, v68
	v_mov_b32_e32 v71, v72
	v_pk_mul_f32 v[16:17], v[16:17], v[18:19] op_sel_hi:[1,0]
	v_pk_mul_f32 v[14:15], v[14:15], v[18:19] op_sel_hi:[1,0]
	v_pk_mul_f32 v[22:23], v[12:13], v[20:21]
	v_pk_mul_f32 v[26:27], v[10:11], v[24:25]
	v_pk_mul_f32 v[12:13], v[12:13], v[70:71]
	v_pk_mul_f32 v[10:11], v[10:11], v[66:67]
	v_pk_fma_f32 v[12:13], v[16:17], v[20:21], v[12:13]
	v_pk_fma_f32 v[10:11], v[14:15], v[24:25], v[10:11]
	v_pk_fma_f32 v[26:27], v[14:15], v[66:67], v[26:27] neg_lo:[0,0,1] neg_hi:[0,0,1]
	v_cvt_pk_bf16_f32 v10, v10, v11
	v_cvt_pk_bf16_f32 v11, v12, v13
	v_or_b32_e32 v12, v58, v19
	v_mad_u64_u32 v[12:13], s[38:39], v12, s73, v[122:123]
	v_mad_i32_i24 v13, v59, s73, v13
	v_lshl_add_u64 v[12:13], v[12:13], 0, v[124:125]
	v_pk_fma_f32 v[22:23], v[16:17], v[70:71], v[22:23] neg_lo:[0,0,1] neg_hi:[0,0,1]
	v_lshl_add_u64 v[16:17], v[12:13], 0, s[22:23]
	v_add_co_u32_e32 v12, vcc, s74, v12
	v_cvt_pk_bf16_f32 v14, v26, v27
	v_cvt_pk_bf16_f32 v15, v22, v23
	v_addc_co_u32_e32 v13, vcc, 0, v13, vcc
	v_pk_mul_f32 v[2:3], v[2:3], v[18:19] op_sel_hi:[1,0]
	v_pk_mul_f32 v[4:5], v[4:5], v[18:19] op_sel_hi:[1,0]
	global_store_dwordx2 v[12:13], v[14:15], off offset:256
	global_store_dwordx2 v[16:17], v[10:11], off offset:64
	v_pk_mul_f32 v[8:9], v[8:9], v[18:19] op_sel_hi:[1,0]
	v_pk_mul_f32 v[6:7], v[6:7], v[18:19] op_sel_hi:[1,0]
	v_pk_mul_f32 v[10:11], v[4:5], v[20:21]
	v_pk_mul_f32 v[12:13], v[2:3], v[24:25]
	v_pk_mul_f32 v[4:5], v[4:5], v[70:71]
	v_pk_mul_f32 v[2:3], v[2:3], v[66:67]
	v_pk_fma_f32 v[4:5], v[8:9], v[20:21], v[4:5]
	v_pk_fma_f32 v[2:3], v[6:7], v[24:25], v[2:3]
	v_pk_fma_f32 v[12:13], v[6:7], v[66:67], v[12:13] neg_lo:[0,0,1] neg_hi:[0,0,1]
	v_cvt_pk_bf16_f32 v2, v2, v3
	v_cvt_pk_bf16_f32 v3, v4, v5
	v_or_b32_e32 v4, v50, v19
	v_mad_u64_u32 v[4:5], s[38:39], v4, s73, v[122:123]
	v_mad_i32_i24 v5, v51, s73, v5
	v_lshl_add_u64 v[4:5], v[4:5], 0, v[124:125]
	v_pk_fma_f32 v[10:11], v[8:9], v[70:71], v[10:11] neg_lo:[0,0,1] neg_hi:[0,0,1]
	v_lshl_add_u64 v[8:9], v[4:5], 0, s[22:23]
	v_add_co_u32_e32 v4, vcc, 0x9100000, v4
	v_cvt_pk_bf16_f32 v6, v12, v13
	v_cvt_pk_bf16_f32 v7, v10, v11
	v_addc_co_u32_e32 v5, vcc, 0, v5, vcc
	global_store_dwordx2 v[4:5], v[6:7], off offset:256
	global_store_dwordx2 v[8:9], v[2:3], off offset:64
	s_andn2_b64 vcc, exec, s[36:37]
	s_mov_b64 s[36:37], -1
	s_cbranch_vccnz .LBB0_429

; __device__ __forceinline__ u32x4 pack8(const f32x4 a, const f32x4 b) { u32x4 w; w.x = cvt_pk_bf16(a[0], a[1]); w.y = cvt_pk_bf16(a[2], a[3]); w.z = cvt_pk_bf16(b[0], b[1]); w.w = cvt_pk_bf16(b[2], b[3]); return w; }
;     __device__ __forceinline__ void operator()(f32x4 (&acc)[2][2][4][2], const Unit& u, int wr, int wc, int fr, int fq) const {
;     ...
;                         } else if (kind == K_KV) { const float sc = rsqrtf(rsv[ai * 4 + m] * (1.0f / 512.0f) + EPS); const int h = u.pn, b = row >> 12, pos = NMETA + (row & 4095);
; #pragma unroll
;                             for (int bj = 0; bj < 2; ++bj) *(u32x4*)((bj == 0 ? P.kn_() : P.v_()) + ((size_t)(b * NH + h) * LPAD + pos) * 128 + c8) = pack8(acc[ai][bj][m][0] * sc, acc[ai][bj][m][1] * sc);
.LBB0_498:
	s_cmp_eq_u32 s72, 7
	s_mov_b64 s[60:61], -1
	s_cbranch_scc0 .LBB0_500
	s_movk_i32 s38, 0xfcf
	v_and_or_b32 v148, v166, s38, 16
	v_rsq_f32_e32 v130, v171
	s_add_i32 s38, s5, s57
	s_mov_b64 s[60:61], 0
	v_mov_b32_e32 v134, v130
	v_mad_i64_i32 v[130:131], s[38:39], s38, v182, v[148:149]
	v_lshlrev_b64 v[136:137], 8, v[130:131]
	v_pk_mul_f32 v[132:133], v[128:129], v[134:135] op_sel_hi:[1,0]
	v_pk_mul_f32 v[130:131], v[126:127], v[134:135] op_sel_hi:[1,0]
	v_pk_mul_f32 v[138:139], v[124:125], v[134:135] op_sel_hi:[1,0]
	v_pk_mul_f32 v[140:141], v[122:123], v[134:135] op_sel_hi:[1,0]
	v_cvt_pk_bf16_f32 v130, v130, v131
	v_cvt_pk_bf16_f32 v131, v132, v133
	v_cvt_pk_bf16_f32 v132, v140, v141
	v_cvt_pk_bf16_f32 v133, v138, v139
	v_lshl_add_u64 v[138:139], v[152:153], 0, v[136:137]
	global_store_dwordx4 v[138:139], v[130:133], off
	v_pk_mul_f32 v[138:139], v[116:117], v[134:135] op_sel_hi:[1,0]
	s_nop 0
	v_pk_mul_f32 v[132:133], v[120:121], v[134:135] op_sel_hi:[1,0]
	v_pk_mul_f32 v[130:131], v[118:119], v[134:135] op_sel_hi:[1,0]
	v_pk_mul_f32 v[134:135], v[114:115], v[134:135] op_sel_hi:[1,0]
	v_cvt_pk_bf16_f32 v130, v130, v131
	v_cvt_pk_bf16_f32 v131, v132, v133
	v_cvt_pk_bf16_f32 v132, v134, v135
	v_cvt_pk_bf16_f32 v133, v138, v139
	v_lshl_add_u64 v[134:135], v[154:155], 0, v[136:137]
	global_store_dwordx4 v[134:135], v[130:133], off

; __device__ __forceinline__ u32x4 pack8(const f32x4 a, const f32x4 b) { u32x4 w; w.x = cvt_pk_bf16(a[0], a[1]); w.y = cvt_pk_bf16(a[2], a[3]); w.z = cvt_pk_bf16(b[0], b[1]); w.w = cvt_pk_bf16(b[2], b[3]); return w; }
;     __device__ __forceinline__ void operator()(f32x4 (&acc)[2][2][4][2], const Unit& u, int wr, int wc, int fr, int fq) const {
;     ...
;                         } else if (kind == K_KV) { const float sc = rsqrtf(rsv[ai * 4 + m] * (1.0f / 512.0f) + EPS); const int h = u.pn, b = row >> 12, pos = NMETA + (row & 4095);
; #pragma unroll
;                             for (int bj = 0; bj < 2; ++bj) *(u32x4*)((bj == 0 ? P.kn_() : P.v_()) + ((size_t)(b * NH + h) * LPAD + pos) * 128 + c8) = pack8(acc[ai][bj][m][0] * sc, acc[ai][bj][m][1] * sc);
.LBB0_503:
	s_cmp_eq_u32 s72, 7
	s_mov_b64 s[60:61], -1
	s_cbranch_scc0 .LBB0_505
	v_and_b32_e32 v132, 0xfdf, v130
	v_add_u32_e32 v148, 16, v132
	v_rsq_f32_e32 v131, v170
	s_add_i32 s38, s5, s57
	s_mov_b64 s[60:61], 0
	v_mov_b32_e32 v136, v131
	v_mad_i64_i32 v[132:133], s[38:39], s38, v182, v[148:149]
	v_lshlrev_b64 v[138:139], 8, v[132:133]
	v_pk_mul_f32 v[134:135], v[112:113], v[136:137] op_sel_hi:[1,0]
	v_pk_mul_f32 v[132:133], v[110:111], v[136:137] op_sel_hi:[1,0]
	v_pk_mul_f32 v[140:141], v[108:109], v[136:137] op_sel_hi:[1,0]
	v_pk_mul_f32 v[142:143], v[106:107], v[136:137] op_sel_hi:[1,0]
	v_cvt_pk_bf16_f32 v132, v132, v133
	v_cvt_pk_bf16_f32 v133, v134, v135
	v_cvt_pk_bf16_f32 v134, v142, v143
	v_cvt_pk_bf16_f32 v135, v140, v141
	v_lshl_add_u64 v[140:141], v[152:153], 0, v[138:139]
	global_store_dwordx4 v[140:141], v[132:135], off
	v_pk_mul_f32 v[140:141], v[100:101], v[136:137] op_sel_hi:[1,0]
	s_nop 0
	v_pk_mul_f32 v[134:135], v[104:105], v[136:137] op_sel_hi:[1,0]
	v_pk_mul_f32 v[132:133], v[102:103], v[136:137] op_sel_hi:[1,0]
	v_pk_mul_f32 v[136:137], v[98:99], v[136:137] op_sel_hi:[1,0]
	v_cvt_pk_bf16_f32 v132, v132, v133
	v_cvt_pk_bf16_f32 v133, v134, v135
	v_cvt_pk_bf16_f32 v134, v136, v137
	v_cvt_pk_bf16_f32 v135, v140, v141
	v_lshl_add_u64 v[136:137], v[154:155], 0, v[138:139]
	global_store_dwordx4 v[136:137], v[132:135], off

; __device__ __forceinline__ u32x4 pack8(const f32x4 a, const f32x4 b) { u32x4 w; w.x = cvt_pk_bf16(a[0], a[1]); w.y = cvt_pk_bf16(a[2], a[3]); w.z = cvt_pk_bf16(b[0], b[1]); w.w = cvt_pk_bf16(b[2], b[3]); return w; }
;     __device__ __forceinline__ void operator()(f32x4 (&acc)[2][2][4][2], const Unit& u, int wr, int wc, int fr, int fq) const {
;     ...
;                         } else if (kind == K_KV) { const float sc = rsqrtf(rsv[ai * 4 + m] * (1.0f / 512.0f) + EPS); const int h = u.pn, b = row >> 12, pos = NMETA + (row & 4095);
; #pragma unroll
;                             for (int bj = 0; bj < 2; ++bj) *(u32x4*)((bj == 0 ? P.kn_() : P.v_()) + ((size_t)(b * NH + h) * LPAD + pos) * 128 + c8) = pack8(acc[ai][bj][m][0] * sc, acc[ai][bj][m][1] * sc);
.LBB0_508:
	s_cmp_eq_u32 s72, 7
	s_mov_b64 s[60:61], -1
	s_cbranch_scc0 .LBB0_510
	s_movk_i32 s38, 0xfef
	v_and_or_b32 v148, v130, s38, 16
	v_rsq_f32_e32 v131, v169
	s_add_i32 s38, s5, s57
	s_mov_b64 s[60:61], 0
	v_mov_b32_e32 v136, v131
	v_mad_i64_i32 v[132:133], s[38:39], s38, v182, v[148:149]
	v_lshlrev_b64 v[138:139], 8, v[132:133]
	v_pk_mul_f32 v[134:135], v[96:97], v[136:137] op_sel_hi:[1,0]
	v_pk_mul_f32 v[132:133], v[94:95], v[136:137] op_sel_hi:[1,0]
	v_pk_mul_f32 v[140:141], v[92:93], v[136:137] op_sel_hi:[1,0]
	v_pk_mul_f32 v[142:143], v[90:91], v[136:137] op_sel_hi:[1,0]
	v_cvt_pk_bf16_f32 v132, v132, v133
	v_cvt_pk_bf16_f32 v133, v134, v135
	v_cvt_pk_bf16_f32 v134, v142, v143
	v_cvt_pk_bf16_f32 v135, v140, v141
	v_lshl_add_u64 v[140:141], v[152:153], 0, v[138:139]
	global_store_dwordx4 v[140:141], v[132:135], off
	v_pk_mul_f32 v[140:141], v[84:85], v[136:137] op_sel_hi:[1,0]
	s_nop 0
	v_pk_mul_f32 v[134:135], v[88:89], v[136:137] op_sel_hi:[1,0]
	v_pk_mul_f32 v[132:133], v[86:87], v[136:137] op_sel_hi:[1,0]
	v_pk_mul_f32 v[136:137], v[82:83], v[136:137] op_sel_hi:[1,0]
	v_cvt_pk_bf16_f32 v132, v132, v133
	v_cvt_pk_bf16_f32 v133, v134, v135
	v_cvt_pk_bf16_f32 v134, v136, v137
	v_cvt_pk_bf16_f32 v135, v140, v141
	v_lshl_add_u64 v[136:137], v[154:155], 0, v[138:139]
	global_store_dwordx4 v[136:137], v[132:135], off

; __device__ __forceinline__ u32x4 pack8(const f32x4 a, const f32x4 b) { u32x4 w; w.x = cvt_pk_bf16(a[0], a[1]); w.y = cvt_pk_bf16(a[2], a[3]); w.z = cvt_pk_bf16(b[0], b[1]); w.w = cvt_pk_bf16(b[2], b[3]); return w; }
;     __device__ __forceinline__ void operator()(f32x4 (&acc)[2][2][4][2], const Unit& u, int wr, int wc, int fr, int fq) const {
;     ...
;                         } else if (kind == K_KV) { const float sc = rsqrtf(rsv[ai * 4 + m] * (1.0f / 512.0f) + EPS); const int h = u.pn, b = row >> 12, pos = NMETA + (row & 4095);
; #pragma unroll
;                             for (int bj = 0; bj < 2; ++bj) *(u32x4*)((bj == 0 ? P.kn_() : P.v_()) + ((size_t)(b * NH + h) * LPAD + pos) * 128 + c8) = pack8(acc[ai][bj][m][0] * sc, acc[ai][bj][m][1] * sc);
.LBB0_513:
	s_cmp_eq_u32 s72, 7
	s_mov_b64 s[60:61], -1
	s_cbranch_scc0 .LBB0_515
	v_and_b32_e32 v132, 0xfff, v130
	v_add_u32_e32 v148, 16, v132
	v_rsq_f32_e32 v131, v168
	s_add_i32 s38, s5, s57
	s_mov_b64 s[60:61], 0
	v_mov_b32_e32 v136, v131
	v_mad_i64_i32 v[132:133], s[38:39], s38, v182, v[148:149]
	v_lshlrev_b64 v[138:139], 8, v[132:133]
	v_pk_mul_f32 v[134:135], v[80:81], v[136:137] op_sel_hi:[1,0]
	v_pk_mul_f32 v[132:133], v[78:79], v[136:137] op_sel_hi:[1,0]
	v_pk_mul_f32 v[140:141], v[76:77], v[136:137] op_sel_hi:[1,0]
	v_pk_mul_f32 v[142:143], v[74:75], v[136:137] op_sel_hi:[1,0]
	v_cvt_pk_bf16_f32 v132, v132, v133
	v_cvt_pk_bf16_f32 v133, v134, v135
	v_cvt_pk_bf16_f32 v134, v142, v143
	v_cvt_pk_bf16_f32 v135, v140, v141
	v_lshl_add_u64 v[140:141], v[152:153], 0, v[138:139]
	global_store_dwordx4 v[140:141], v[132:135], off
	v_pk_mul_f32 v[140:141], v[68:69], v[136:137] op_sel_hi:[1,0]
	s_nop 0
	v_pk_mul_f32 v[134:135], v[72:73], v[136:137] op_sel_hi:[1,0]
	v_pk_mul_f32 v[132:133], v[70:71], v[136:137] op_sel_hi:[1,0]
	v_pk_mul_f32 v[136:137], v[66:67], v[136:137] op_sel_hi:[1,0]
	v_cvt_pk_bf16_f32 v132, v132, v133
	v_cvt_pk_bf16_f32 v133, v134, v135
	v_cvt_pk_bf16_f32 v134, v136, v137
	v_cvt_pk_bf16_f32 v135, v140, v141
	v_lshl_add_u64 v[136:137], v[154:155], 0, v[138:139]
	global_store_dwordx4 v[136:137], v[132:135], off

; __device__ __forceinline__ u32x4 pack8(const f32x4 a, const f32x4 b) { u32x4 w; w.x = cvt_pk_bf16(a[0], a[1]); w.y = cvt_pk_bf16(a[2], a[3]); w.z = cvt_pk_bf16(b[0], b[1]); w.w = cvt_pk_bf16(b[2], b[3]); return w; }
;     __device__ __forceinline__ void operator()(f32x4 (&acc)[2][2][4][2], const Unit& u, int wr, int wc, int fr, int fq) const {
;     ...
;                         } else if (kind == K_KV) { const float sc = rsqrtf(rsv[ai * 4 + m] * (1.0f / 512.0f) + EPS); const int h = u.pn, b = row >> 12, pos = NMETA + (row & 4095);
; #pragma unroll
;                             for (int bj = 0; bj < 2; ++bj) *(u32x4*)((bj == 0 ? P.kn_() : P.v_()) + ((size_t)(b * NH + h) * LPAD + pos) * 128 + c8) = pack8(acc[ai][bj][m][0] * sc, acc[ai][bj][m][1] * sc);
.LBB0_518:
	s_cmp_eq_u32 s72, 7
	s_mov_b64 s[60:61], -1
	s_cbranch_scc0 .LBB0_520
	s_movk_i32 s5, 0xfcf
	v_and_or_b32 v148, v131, s5, 16
	v_rsq_f32_e32 v130, v165
	v_add_u32_e32 v133, s57, v132
	s_movk_i32 s5, 0x1040
	s_mov_b64 s[60:61], 0
	v_mad_i64_i32 v[134:135], s[38:39], v133, s5, v[148:149]
	v_lshlrev_b64 v[138:139], 8, v[134:135]
	v_pk_mul_f32 v[136:137], v[64:65], v[130:131] op_sel_hi:[1,0]
	v_pk_mul_f32 v[134:135], v[62:63], v[130:131] op_sel_hi:[1,0]
	v_pk_mul_f32 v[140:141], v[60:61], v[130:131] op_sel_hi:[1,0]
	v_pk_mul_f32 v[142:143], v[58:59], v[130:131] op_sel_hi:[1,0]
	v_cvt_pk_bf16_f32 v134, v134, v135
	v_cvt_pk_bf16_f32 v135, v136, v137
	v_cvt_pk_bf16_f32 v136, v142, v143
	v_cvt_pk_bf16_f32 v137, v140, v141
	v_lshl_add_u64 v[140:141], v[152:153], 0, v[138:139]
	global_store_dwordx4 v[140:141], v[134:137], off
	v_pk_mul_f32 v[140:141], v[52:53], v[130:131] op_sel_hi:[1,0]
	v_pk_mul_f32 v[142:143], v[50:51], v[130:131] op_sel_hi:[1,0]
	v_pk_mul_f32 v[136:137], v[56:57], v[130:131] op_sel_hi:[1,0]
	v_pk_mul_f32 v[134:135], v[54:55], v[130:131] op_sel_hi:[1,0]
	v_lshl_add_u64 v[138:139], v[154:155], 0, v[138:139]
	v_cvt_pk_bf16_f32 v134, v134, v135
	v_cvt_pk_bf16_f32 v135, v136, v137
	v_cvt_pk_bf16_f32 v136, v142, v143
	v_cvt_pk_bf16_f32 v137, v140, v141
	global_store_dwordx4 v[138:139], v[134:137], off

; __device__ __forceinline__ u32x4 pack8(const f32x4 a, const f32x4 b) { u32x4 w; w.x = cvt_pk_bf16(a[0], a[1]); w.y = cvt_pk_bf16(a[2], a[3]); w.z = cvt_pk_bf16(b[0], b[1]); w.w = cvt_pk_bf16(b[2], b[3]); return w; }
;     __device__ __forceinline__ void operator()(f32x4 (&acc)[2][2][4][2], const Unit& u, int wr, int wc, int fr, int fq) const {
;     ...
;                         } else if (kind == K_KV) { const float sc = rsqrtf(rsv[ai * 4 + m] * (1.0f / 512.0f) + EPS); const int h = u.pn, b = row >> 12, pos = NMETA + (row & 4095);
; #pragma unroll
;                             for (int bj = 0; bj < 2; ++bj) *(u32x4*)((bj == 0 ? P.kn_() : P.v_()) + ((size_t)(b * NH + h) * LPAD + pos) * 128 + c8) = pack8(acc[ai][bj][m][0] * sc, acc[ai][bj][m][1] * sc);
.LBB0_523:
	s_cmp_eq_u32 s72, 7
	s_mov_b64 s[60:61], -1
	s_cbranch_scc0 .LBB0_525
	v_and_b32_e32 v134, 0xfdf, v131
	v_add_u32_e32 v148, 16, v134
	v_rsq_f32_e32 v133, v164
	s_movk_i32 s5, 0x1040
	s_mov_b64 s[60:61], 0
	v_mov_b32_e32 v138, v133
	v_add_u32_e32 v133, s57, v132
	v_mad_i64_i32 v[134:135], s[38:39], v133, s5, v[148:149]
	v_lshlrev_b64 v[140:141], 8, v[134:135]
	v_pk_mul_f32 v[136:137], v[48:49], v[138:139] op_sel_hi:[1,0]
	v_pk_mul_f32 v[134:135], v[46:47], v[138:139] op_sel_hi:[1,0]
	v_pk_mul_f32 v[142:143], v[44:45], v[138:139] op_sel_hi:[1,0]
	v_pk_mul_f32 v[144:145], v[42:43], v[138:139] op_sel_hi:[1,0]
	v_cvt_pk_bf16_f32 v134, v134, v135
	v_cvt_pk_bf16_f32 v135, v136, v137
	v_cvt_pk_bf16_f32 v136, v144, v145
	v_cvt_pk_bf16_f32 v137, v142, v143
	v_lshl_add_u64 v[142:143], v[152:153], 0, v[140:141]
	global_store_dwordx4 v[142:143], v[134:137], off
	v_pk_mul_f32 v[142:143], v[36:37], v[138:139] op_sel_hi:[1,0]
	s_nop 0
	v_pk_mul_f32 v[136:137], v[40:41], v[138:139] op_sel_hi:[1,0]
	v_pk_mul_f32 v[134:135], v[38:39], v[138:139] op_sel_hi:[1,0]
	v_pk_mul_f32 v[138:139], v[34:35], v[138:139] op_sel_hi:[1,0]
	v_cvt_pk_bf16_f32 v134, v134, v135
	v_cvt_pk_bf16_f32 v135, v136, v137
	v_cvt_pk_bf16_f32 v136, v138, v139
	v_cvt_pk_bf16_f32 v137, v142, v143
	v_lshl_add_u64 v[138:139], v[154:155], 0, v[140:141]
	global_store_dwordx4 v[138:139], v[134:137], off

; __device__ __forceinline__ u32x4 pack8(const f32x4 a, const f32x4 b) { u32x4 w; w.x = cvt_pk_bf16(a[0], a[1]); w.y = cvt_pk_bf16(a[2], a[3]); w.z = cvt_pk_bf16(b[0], b[1]); w.w = cvt_pk_bf16(b[2], b[3]); return w; }
;     __device__ __forceinline__ void operator()(f32x4 (&acc)[2][2][4][2], const Unit& u, int wr, int wc, int fr, int fq) const {
;     ...
;                         } else if (kind == K_KV) { const float sc = rsqrtf(rsv[ai * 4 + m] * (1.0f / 512.0f) + EPS); const int h = u.pn, b = row >> 12, pos = NMETA + (row & 4095);
; #pragma unroll
;                             for (int bj = 0; bj < 2; ++bj) *(u32x4*)((bj == 0 ? P.kn_() : P.v_()) + ((size_t)(b * NH + h) * LPAD + pos) * 128 + c8) = pack8(acc[ai][bj][m][0] * sc, acc[ai][bj][m][1] * sc);
.LBB0_528:
	s_cmp_eq_u32 s72, 7
	s_mov_b64 s[60:61], -1
	s_cbranch_scc0 .LBB0_530
	s_movk_i32 s5, 0xfef
	v_and_or_b32 v148, v131, s5, 16
	v_rsq_f32_e32 v133, v163
	v_add_u32_e32 v134, s57, v132
	s_movk_i32 s5, 0x1040
	s_mov_b64 s[60:61], 0
	v_mov_b32_e32 v138, v133
	v_mad_i64_i32 v[134:135], s[38:39], v134, s5, v[148:149]
	v_lshlrev_b64 v[140:141], 8, v[134:135]
	v_pk_mul_f32 v[136:137], v[32:33], v[138:139] op_sel_hi:[1,0]
	v_pk_mul_f32 v[134:135], v[30:31], v[138:139] op_sel_hi:[1,0]
	v_pk_mul_f32 v[142:143], v[28:29], v[138:139] op_sel_hi:[1,0]
	v_pk_mul_f32 v[144:145], v[26:27], v[138:139] op_sel_hi:[1,0]
	v_cvt_pk_bf16_f32 v134, v134, v135
	v_cvt_pk_bf16_f32 v135, v136, v137
	v_cvt_pk_bf16_f32 v136, v144, v145
	v_cvt_pk_bf16_f32 v137, v142, v143
	v_lshl_add_u64 v[142:143], v[152:153], 0, v[140:141]
	global_store_dwordx4 v[142:143], v[134:137], off
	v_pk_mul_f32 v[142:143], v[20:21], v[138:139] op_sel_hi:[1,0]
	s_nop 0
	v_pk_mul_f32 v[136:137], v[24:25], v[138:139] op_sel_hi:[1,0]
	v_pk_mul_f32 v[134:135], v[22:23], v[138:139] op_sel_hi:[1,0]
	v_pk_mul_f32 v[138:139], v[18:19], v[138:139] op_sel_hi:[1,0]
	v_cvt_pk_bf16_f32 v134, v134, v135
	v_cvt_pk_bf16_f32 v135, v136, v137
	v_cvt_pk_bf16_f32 v136, v138, v139
	v_cvt_pk_bf16_f32 v137, v142, v143
	v_lshl_add_u64 v[138:139], v[154:155], 0, v[140:141]
	global_store_dwordx4 v[138:139], v[134:137], off

; __device__ __forceinline__ u32x4 pack8(const f32x4 a, const f32x4 b) { u32x4 w; w.x = cvt_pk_bf16(a[0], a[1]); w.y = cvt_pk_bf16(a[2], a[3]); w.z = cvt_pk_bf16(b[0], b[1]); w.w = cvt_pk_bf16(b[2], b[3]); return w; }
;     __device__ __forceinline__ void operator()(f32x4 (&acc)[2][2][4][2], const Unit& u, int wr, int wc, int fr, int fq) const {
;     ...
;                         } else if (kind == K_KV) { const float sc = rsqrtf(rsv[ai * 4 + m] * (1.0f / 512.0f) + EPS); const int h = u.pn, b = row >> 12, pos = NMETA + (row & 4095);
; #pragma unroll
;                             for (int bj = 0; bj < 2; ++bj) *(u32x4*)((bj == 0 ? P.kn_() : P.v_()) + ((size_t)(b * NH + h) * LPAD + pos) * 128 + c8) = pack8(acc[ai][bj][m][0] * sc, acc[ai][bj][m][1] * sc);
.LBB0_533:
	s_cmp_eq_u32 s72, 7
	s_mov_b64 s[60:61], -1
	s_cbranch_scc0 .LBB0_535
	v_and_b32_e32 v134, 0xfff, v131
	v_add_u32_e32 v148, 16, v134
	v_rsq_f32_e32 v133, v162
	v_add_u32_e32 v132, s57, v132
	s_movk_i32 s5, 0x1040
	s_mov_b64 s[60:61], 0
	v_mov_b32_e32 v136, v133
	v_mad_i64_i32 v[132:133], s[38:39], v132, s5, v[148:149]
	v_lshlrev_b64 v[138:139], 8, v[132:133]
	v_pk_mul_f32 v[134:135], v[16:17], v[136:137] op_sel_hi:[1,0]
	v_pk_mul_f32 v[132:133], v[14:15], v[136:137] op_sel_hi:[1,0]
	v_pk_mul_f32 v[140:141], v[12:13], v[136:137] op_sel_hi:[1,0]
	v_pk_mul_f32 v[142:143], v[10:11], v[136:137] op_sel_hi:[1,0]
	v_cvt_pk_bf16_f32 v132, v132, v133
	v_cvt_pk_bf16_f32 v133, v134, v135
	v_cvt_pk_bf16_f32 v134, v142, v143
	v_cvt_pk_bf16_f32 v135, v140, v141
	v_lshl_add_u64 v[140:141], v[152:153], 0, v[138:139]
	global_store_dwordx4 v[140:141], v[132:135], off
	v_pk_mul_f32 v[140:141], v[4:5], v[136:137] op_sel_hi:[1,0]
	s_nop 0
	v_pk_mul_f32 v[134:135], v[8:9], v[136:137] op_sel_hi:[1,0]
	v_pk_mul_f32 v[132:133], v[6:7], v[136:137] op_sel_hi:[1,0]
	v_pk_mul_f32 v[136:137], v[2:3], v[136:137] op_sel_hi:[1,0]
	v_cvt_pk_bf16_f32 v132, v132, v133
	v_cvt_pk_bf16_f32 v133, v134, v135
	v_cvt_pk_bf16_f32 v134, v136, v137
	v_cvt_pk_bf16_f32 v135, v140, v141
	v_lshl_add_u64 v[136:137], v[154:155], 0, v[138:139]
	global_store_dwordx4 v[136:137], v[132:135], off

; #define SBAR() __builtin_amdgcn_sched_barrier(0)
; __device__ __forceinline__ float fast_sigmoid(float x) { return __builtin_amdgcn_rcpf(1.0f + __builtin_amdgcn_exp2f(-1.4426950408889634f * x)); }
; __device__ __forceinline__ u32x4 pack8(const f32x4 a, const f32x4 b) { u32x4 w; w.x = cvt_pk_bf16(a[0], a[1]); w.y = cvt_pk_bf16(a[2], a[3]); w.z = cvt_pk_bf16(b[0], b[1]); w.w = cvt_pk_bf16(b[2], b[3]); return w; }
;     __device__ __forceinline__ void operator()(f32x4 (&acc)[2][2][4][2], const Unit& u, int wr, int wc, int fr, int fq) const {
;     ...
;             float rsv[8];
; #pragma unroll
;             for (int i = 0; i < 8; ++i) rsv[i] = P.ssq_h1_()[ROWOF(i >> 2, i & 3)];
;             SBAR();
; #pragma unroll
;             for (int ai = 0; ai < 2; ++ai)
; #pragma unroll
;                 for (int m = 0; m < 4; ++m) { const int row = ROWOF(ai, m); const float rs = rsqrtf(rsv[ai * 4 + m] * (1.0f / 2048.0f) + EPS);
;                     f32x4 g0 = acc[ai][0][m][0] * rs, g1 = acc[ai][0][m][1] * rs; const f32x4 u0 = acc[ai][1][m][0] * rs, u1 = acc[ai][1][m][1] * rs;
; #pragma unroll
;                     for (int j = 0; j < 4; ++j) { g0[j] = g0[j] * fast_sigmoid(g0[j]) * u0[j]; g1[j] = g1[j] * fast_sigmoid(g1[j]) * u1[j]; }
;                     *(u32x4*)(P.f_() + (size_t)row * DFF + u.pn * 128 + c8) = pack8(g0, g1); }
.LBB0_1002:
	v_lshl_add_u32 v146, s22, 8, v150
	v_ashrrev_i32_e32 v147, 31, v146
	v_lshl_add_u64 v[156:157], v[146:147], 2, s[10:11]
	global_load_dword v158, v[156:157], off
	global_load_dword v159, v[156:157], off offset:64
	global_load_dword v164, v[156:157], off offset:128
	global_load_dword v165, v[156:157], off offset:192
	global_load_dword v166, v[156:157], off offset:512
	global_load_dword v149, v[156:157], off offset:576
	global_load_dword v148, v[156:157], off offset:640
	global_load_dword v147, v[156:157], off offset:704
	v_add_u32_e32 v156, 0x80, v146
	s_waitcnt vmcnt(0)
	v_fmamk_f32 v157, v158, 0x3a000000, v155
	s_lshl_b32 s22, s23, 7
	s_ashr_i32 s23, s22, 31
	v_rsq_f32_e32 v157, v157
	s_lshl_b64 s[22:23], s[22:23], 1
	v_mov_b32_e32 v158, v157
	v_pk_mul_f32 v[126:127], v[126:127], v[158:159] op_sel_hi:[1,0]
	v_pk_mul_f32 v[122:123], v[122:123], v[158:159] op_sel_hi:[1,0]
	v_mul_f32_e32 v157, 0xbfb8aa3b, v126
	v_mul_f32_e32 v160, 0xbfb8aa3b, v122
	v_exp_f32_e32 v157, v157
	v_exp_f32_e32 v161, v160
	v_mul_f32_e32 v160, 0xbfb8aa3b, v127
	v_exp_f32_e32 v162, v160
	v_add_f32_e32 v157, 1.0, v157
	v_rcp_f32_e32 v160, v157
	v_add_f32_e32 v157, 1.0, v161
	v_add_f32_e32 v161, 1.0, v162
	v_mul_f32_e32 v162, 0xbfb8aa3b, v123
	v_exp_f32_e32 v163, v162
	v_rcp_f32_e32 v161, v161
	v_rcp_f32_e32 v162, v157
	v_pk_mul_f32 v[128:129], v[128:129], v[158:159] op_sel_hi:[1,0]
	v_add_f32_e32 v157, 1.0, v163
	v_rcp_f32_e32 v163, v157
	v_pk_mul_f32 v[126:127], v[126:127], v[160:161]
	v_pk_mul_f32 v[118:119], v[118:119], v[158:159] op_sel_hi:[1,0]
	v_pk_mul_f32 v[124:125], v[124:125], v[158:159] op_sel_hi:[1,0]
	v_pk_mul_f32 v[118:119], v[118:119], v[126:127]
	v_mul_f32_e32 v126, 0xbfb8aa3b, v128
	v_pk_mul_f32 v[122:123], v[122:123], v[162:163]
	v_pk_mul_f32 v[114:115], v[114:115], v[158:159] op_sel_hi:[1,0]
	v_exp_f32_e32 v126, v126
	v_pk_mul_f32 v[114:115], v[114:115], v[122:123]
	v_mul_f32_e32 v123, 0xbfb8aa3b, v124
	v_exp_f32_e32 v123, v123
	v_add_f32_e32 v122, 1.0, v126
	v_mul_f32_e32 v126, 0xbfb8aa3b, v129
	v_exp_f32_e32 v126, v126
	v_add_f32_e32 v127, 1.0, v123
	v_mul_f32_e32 v123, 0xbfb8aa3b, v125
	v_exp_f32_e32 v157, v123
	v_add_f32_e32 v123, 1.0, v126
	v_rcp_f32_e32 v122, v122
	v_rcp_f32_e32 v123, v123
	v_rcp_f32_e32 v126, v127
	v_add_f32_e32 v127, 1.0, v157
	v_rcp_f32_e32 v127, v127
	v_pk_mul_f32 v[122:123], v[128:129], v[122:123]
	v_pk_mul_f32 v[120:121], v[120:121], v[158:159] op_sel_hi:[1,0]
	v_pk_mul_f32 v[116:117], v[116:117], v[158:159] op_sel_hi:[1,0]
	v_pk_mul_f32 v[120:121], v[120:121], v[122:123]
	v_pk_mul_f32 v[122:123], v[124:125], v[126:127]
	s_nop 0
	v_pk_mul_f32 v[122:123], v[116:117], v[122:123]
	v_cvt_pk_bf16_f32 v116, v118, v119
	v_cvt_pk_bf16_f32 v119, v122, v123
	v_fmamk_f32 v122, v159, 0x3a000000, v155
	v_cvt_pk_bf16_f32 v118, v114, v115
	v_mov_b64_e32 v[114:115], s[12:13]
	v_rsq_f32_e32 v122, v122
	v_cvt_pk_bf16_f32 v117, v120, v121
	v_mad_i64_i32 v[120:121], s[28:29], v146, s52, v[114:115]
	v_lshl_add_u64 v[120:121], v[120:121], 0, s[22:23]
	v_lshl_add_u64 v[120:121], v[120:121], 0, v[134:135]
	global_store_dwordx4 v[120:121], v[116:119], off
	s_nop 1
	v_mov_b32_e32 v116, v122
	v_pk_mul_f32 v[110:111], v[110:111], v[116:117] op_sel_hi:[1,0]
	v_pk_mul_f32 v[106:107], v[106:107], v[116:117] op_sel_hi:[1,0]
	v_pk_mul_f32 v[112:113], v[112:113], v[116:117] op_sel_hi:[1,0]
	v_pk_mul_f32 v[108:109], v[108:109], v[116:117] op_sel_hi:[1,0]
	v_mul_f32_e32 v117, 0xbfb8aa3b, v110
	v_mul_f32_e32 v118, 0xbfb8aa3b, v106
	v_exp_f32_e32 v117, v117
	v_exp_f32_e32 v119, v118
	v_mul_f32_e32 v118, 0xbfb8aa3b, v111
	v_exp_f32_e32 v120, v118
	v_add_f32_e32 v117, 1.0, v117
	v_rcp_f32_e32 v118, v117
	v_add_f32_e32 v117, 1.0, v119
	v_add_f32_e32 v119, 1.0, v120
	v_mul_f32_e32 v120, 0xbfb8aa3b, v107
	v_exp_f32_e32 v121, v120
	v_rcp_f32_e32 v119, v119
	v_rcp_f32_e32 v120, v117
	v_pk_mul_f32 v[102:103], v[102:103], v[116:117] op_sel_hi:[1,0]
	v_add_f32_e32 v117, 1.0, v121
	v_rcp_f32_e32 v121, v117
	v_pk_mul_f32 v[110:111], v[110:111], v[118:119]
	v_pk_mul_f32 v[98:99], v[98:99], v[116:117] op_sel_hi:[1,0]
	v_pk_mul_f32 v[102:103], v[102:103], v[110:111]
	v_mul_f32_e32 v110, 0xbfb8aa3b, v112
	v_pk_mul_f32 v[106:107], v[106:107], v[120:121]
	v_exp_f32_e32 v110, v110
	v_pk_mul_f32 v[106:107], v[98:99], v[106:107]
	v_mul_f32_e32 v99, 0xbfb8aa3b, v108
	v_exp_f32_e32 v99, v99
	v_add_f32_e32 v98, 1.0, v110
	v_mul_f32_e32 v110, 0xbfb8aa3b, v113
	v_exp_f32_e32 v110, v110
	v_add_f32_e32 v111, 1.0, v99
	v_mul_f32_e32 v99, 0xbfb8aa3b, v109
	v_exp_f32_e32 v117, v99
	v_add_f32_e32 v99, 1.0, v110
	v_rcp_f32_e32 v98, v98
	v_rcp_f32_e32 v99, v99
	v_rcp_f32_e32 v110, v111
	v_add_f32_e32 v111, 1.0, v117
	v_rcp_f32_e32 v111, v111
	v_pk_mul_f32 v[98:99], v[112:113], v[98:99]
	v_pk_mul_f32 v[104:105], v[104:105], v[116:117] op_sel_hi:[1,0]
	v_pk_mul_f32 v[100:101], v[100:101], v[116:117] op_sel_hi:[1,0]
	v_pk_mul_f32 v[104:105], v[104:105], v[98:99]
	v_pk_mul_f32 v[98:99], v[108:109], v[110:111]
	v_or_b32_e32 v110, 16, v146
	v_pk_mul_f32 v[108:109], v[100:101], v[98:99]
	v_cvt_pk_bf16_f32 v99, v104, v105
	v_fmamk_f32 v104, v164, 0x3a000000, v155
	v_cvt_pk_bf16_f32 v98, v102, v103
	v_mad_i64_i32 v[102:103], s[28:29], v110, s52, v[114:115]
	v_rsq_f32_e32 v104, v104
	v_lshl_add_u64 v[102:103], v[102:103], 0, s[22:23]
	v_cvt_pk_bf16_f32 v100, v106, v107
	v_cvt_pk_bf16_f32 v101, v108, v109
	v_lshl_add_u64 v[102:103], v[102:103], 0, v[134:135]
	global_store_dwordx4 v[102:103], v[98:101], off
	s_nop 1
	v_mov_b32_e32 v98, v104
	v_pk_mul_f32 v[94:95], v[94:95], v[98:99] op_sel_hi:[1,0]
	v_pk_mul_f32 v[90:91], v[90:91], v[98:99] op_sel_hi:[1,0]
	v_pk_mul_f32 v[96:97], v[96:97], v[98:99] op_sel_hi:[1,0]
; __device__ __forceinline__ float fast_sigmoid(float x) { return __builtin_amdgcn_rcpf(1.0f + __builtin_amdgcn_exp2f(-1.4426950408889634f * x)); }
; __device__ __forceinline__ u32x4 pack8(const f32x4 a, const f32x4 b) { u32x4 w; w.x = cvt_pk_bf16(a[0], a[1]); w.y = cvt_pk_bf16(a[2], a[3]); w.z = cvt_pk_bf16(b[0], b[1]); w.w = cvt_pk_bf16(b[2], b[3]); return w; }
;     __device__ __forceinline__ void operator()(f32x4 (&acc)[2][2][4][2], const Unit& u, int wr, int wc, int fr, int fq) const {
;     ...
;             for (int ai = 0; ai < 2; ++ai)
; #pragma unroll
;                 for (int m = 0; m < 4; ++m) { const int row = ROWOF(ai, m); const float rs = rsqrtf(rsv[ai * 4 + m] * (1.0f / 2048.0f) + EPS);
;                     f32x4 g0 = acc[ai][0][m][0] * rs, g1 = acc[ai][0][m][1] * rs; const f32x4 u0 = acc[ai][1][m][0] * rs, u1 = acc[ai][1][m][1] * rs;
; #pragma unroll
;                     for (int j = 0; j < 4; ++j) { g0[j] = g0[j] * fast_sigmoid(g0[j]) * u0[j]; g1[j] = g1[j] * fast_sigmoid(g1[j]) * u1[j]; }
;                     *(u32x4*)(P.f_() + (size_t)row * DFF + u.pn * 128 + c8) = pack8(g0, g1); }
	v_pk_mul_f32 v[92:93], v[92:93], v[98:99] op_sel_hi:[1,0]
	v_mul_f32_e32 v99, 0xbfb8aa3b, v94
	v_mul_f32_e32 v100, 0xbfb8aa3b, v90
	v_exp_f32_e32 v99, v99
	v_exp_f32_e32 v101, v100
	v_mul_f32_e32 v100, 0xbfb8aa3b, v95
	v_exp_f32_e32 v102, v100
	v_add_f32_e32 v99, 1.0, v99
	v_rcp_f32_e32 v100, v99
	v_add_f32_e32 v99, 1.0, v101
	v_add_f32_e32 v101, 1.0, v102
	v_mul_f32_e32 v102, 0xbfb8aa3b, v91
	v_exp_f32_e32 v103, v102
	v_rcp_f32_e32 v101, v101
	v_rcp_f32_e32 v102, v99
	v_pk_mul_f32 v[86:87], v[86:87], v[98:99] op_sel_hi:[1,0]
	v_add_f32_e32 v99, 1.0, v103
	v_rcp_f32_e32 v103, v99
	v_pk_mul_f32 v[94:95], v[94:95], v[100:101]
	v_pk_mul_f32 v[82:83], v[82:83], v[98:99] op_sel_hi:[1,0]
	v_pk_mul_f32 v[86:87], v[86:87], v[94:95]
	v_mul_f32_e32 v94, 0xbfb8aa3b, v96
	v_pk_mul_f32 v[90:91], v[90:91], v[102:103]
	v_exp_f32_e32 v94, v94
	v_pk_mul_f32 v[90:91], v[82:83], v[90:91]
	v_mul_f32_e32 v83, 0xbfb8aa3b, v92
	v_exp_f32_e32 v83, v83
	v_add_f32_e32 v82, 1.0, v94
	v_mul_f32_e32 v94, 0xbfb8aa3b, v97
	v_exp_f32_e32 v94, v94
	v_add_f32_e32 v95, 1.0, v83
	v_mul_f32_e32 v83, 0xbfb8aa3b, v93
	v_exp_f32_e32 v99, v83
	v_add_f32_e32 v83, 1.0, v94
	v_rcp_f32_e32 v82, v82
	v_rcp_f32_e32 v83, v83
	v_rcp_f32_e32 v94, v95
	v_add_f32_e32 v95, 1.0, v99
	v_rcp_f32_e32 v95, v95
	v_pk_mul_f32 v[82:83], v[96:97], v[82:83]
	v_pk_mul_f32 v[88:89], v[88:89], v[98:99] op_sel_hi:[1,0]
	v_pk_mul_f32 v[84:85], v[84:85], v[98:99] op_sel_hi:[1,0]
	v_pk_mul_f32 v[88:89], v[88:89], v[82:83]
	v_pk_mul_f32 v[82:83], v[92:93], v[94:95]
	v_or_b32_e32 v94, 32, v146
	v_pk_mul_f32 v[92:93], v[84:85], v[82:83]
	v_cvt_pk_bf16_f32 v83, v88, v89
	v_fmamk_f32 v88, v165, 0x3a000000, v155
	v_cvt_pk_bf16_f32 v82, v86, v87
	v_mad_i64_i32 v[86:87], s[28:29], v94, s52, v[114:115]
	v_rsq_f32_e32 v88, v88
	v_lshl_add_u64 v[86:87], v[86:87], 0, s[22:23]
	v_cvt_pk_bf16_f32 v84, v90, v91
	v_cvt_pk_bf16_f32 v85, v92, v93
	v_lshl_add_u64 v[86:87], v[86:87], 0, v[134:135]
	global_store_dwordx4 v[86:87], v[82:85], off
	s_nop 1
	v_mov_b32_e32 v82, v88
	v_pk_mul_f32 v[78:79], v[78:79], v[82:83] op_sel_hi:[1,0]
	v_pk_mul_f32 v[74:75], v[74:75], v[82:83] op_sel_hi:[1,0]
	v_pk_mul_f32 v[80:81], v[80:81], v[82:83] op_sel_hi:[1,0]
	v_pk_mul_f32 v[76:77], v[76:77], v[82:83] op_sel_hi:[1,0]
	v_mul_f32_e32 v83, 0xbfb8aa3b, v78
	v_mul_f32_e32 v84, 0xbfb8aa3b, v74
	v_exp_f32_e32 v83, v83
	v_exp_f32_e32 v85, v84
	v_mul_f32_e32 v84, 0xbfb8aa3b, v79
	v_exp_f32_e32 v86, v84
	v_add_f32_e32 v83, 1.0, v83
	v_rcp_f32_e32 v84, v83
	v_add_f32_e32 v83, 1.0, v85
	v_add_f32_e32 v85, 1.0, v86
	v_mul_f32_e32 v86, 0xbfb8aa3b, v75
	v_exp_f32_e32 v87, v86
	v_rcp_f32_e32 v85, v85
	v_rcp_f32_e32 v86, v83
	v_pk_mul_f32 v[70:71], v[70:71], v[82:83] op_sel_hi:[1,0]
	v_add_f32_e32 v83, 1.0, v87
	v_rcp_f32_e32 v87, v83
	v_pk_mul_f32 v[78:79], v[78:79], v[84:85]
	v_pk_mul_f32 v[66:67], v[66:67], v[82:83] op_sel_hi:[1,0]
	v_pk_mul_f32 v[70:71], v[70:71], v[78:79]
	v_mul_f32_e32 v78, 0xbfb8aa3b, v80
	v_pk_mul_f32 v[74:75], v[74:75], v[86:87]
	v_exp_f32_e32 v78, v78
	v_pk_mul_f32 v[74:75], v[66:67], v[74:75]
	v_mul_f32_e32 v67, 0xbfb8aa3b, v76
	v_exp_f32_e32 v67, v67
	v_add_f32_e32 v66, 1.0, v78
	v_mul_f32_e32 v78, 0xbfb8aa3b, v81
	v_exp_f32_e32 v78, v78
	v_add_f32_e32 v79, 1.0, v67
	v_mul_f32_e32 v67, 0xbfb8aa3b, v77
	v_exp_f32_e32 v83, v67
	v_add_f32_e32 v67, 1.0, v78
	v_rcp_f32_e32 v66, v66
	v_rcp_f32_e32 v67, v67
	v_rcp_f32_e32 v78, v79
	v_add_f32_e32 v79, 1.0, v83
	v_rcp_f32_e32 v79, v79
	v_pk_mul_f32 v[66:67], v[80:81], v[66:67]
	v_pk_mul_f32 v[72:73], v[72:73], v[82:83] op_sel_hi:[1,0]
	v_pk_mul_f32 v[68:69], v[68:69], v[82:83] op_sel_hi:[1,0]
	v_pk_mul_f32 v[72:73], v[72:73], v[66:67]
	v_pk_mul_f32 v[66:67], v[76:77], v[78:79]
	v_or_b32_e32 v78, 48, v146
	v_pk_mul_f32 v[76:77], v[68:69], v[66:67]
	v_cvt_pk_bf16_f32 v67, v72, v73
	v_fmamk_f32 v72, v166, 0x3a000000, v155
	v_cvt_pk_bf16_f32 v66, v70, v71
	v_mad_i64_i32 v[70:71], s[28:29], v78, s52, v[114:115]
	v_rsq_f32_e32 v72, v72
	v_lshl_add_u64 v[70:71], v[70:71], 0, s[22:23]
	v_cvt_pk_bf16_f32 v68, v74, v75
	v_cvt_pk_bf16_f32 v69, v76, v77
	v_lshl_add_u64 v[70:71], v[70:71], 0, v[134:135]
	global_store_dwordx4 v[70:71], v[66:69], off
	s_nop 1
	v_mov_b32_e32 v66, v72
	v_pk_mul_f32 v[62:63], v[62:63], v[66:67] op_sel_hi:[1,0]
	v_pk_mul_f32 v[58:59], v[58:59], v[66:67] op_sel_hi:[1,0]
	v_pk_mul_f32 v[64:65], v[64:65], v[66:67] op_sel_hi:[1,0]
	v_pk_mul_f32 v[60:61], v[60:61], v[66:67] op_sel_hi:[1,0]
	v_mul_f32_e32 v67, 0xbfb8aa3b, v62
	v_mul_f32_e32 v68, 0xbfb8aa3b, v58
	v_exp_f32_e32 v67, v67
	v_exp_f32_e32 v69, v68
	v_mul_f32_e32 v68, 0xbfb8aa3b, v63
	v_exp_f32_e32 v70, v68
	v_add_f32_e32 v67, 1.0, v67
	v_rcp_f32_e32 v68, v67
	v_add_f32_e32 v67, 1.0, v69
	v_add_f32_e32 v69, 1.0, v70
	v_mul_f32_e32 v70, 0xbfb8aa3b, v59
	v_exp_f32_e32 v71, v70
	v_rcp_f32_e32 v69, v69
	v_rcp_f32_e32 v70, v67
	v_pk_mul_f32 v[54:55], v[54:55], v[66:67] op_sel_hi:[1,0]
	v_add_f32_e32 v67, 1.0, v71
	v_rcp_f32_e32 v71, v67
	v_pk_mul_f32 v[62:63], v[62:63], v[68:69]
	v_pk_mul_f32 v[50:51], v[50:51], v[66:67] op_sel_hi:[1,0]
	v_pk_mul_f32 v[54:55], v[54:55], v[62:63]
	v_mul_f32_e32 v62, 0xbfb8aa3b, v64
	v_pk_mul_f32 v[58:59], v[58:59], v[70:71]
	v_exp_f32_e32 v62, v62
	v_pk_mul_f32 v[58:59], v[50:51], v[58:59]
	v_mul_f32_e32 v51, 0xbfb8aa3b, v60
	v_exp_f32_e32 v51, v51
	v_add_f32_e32 v50, 1.0, v62
	v_mul_f32_e32 v62, 0xbfb8aa3b, v65
	v_exp_f32_e32 v62, v62
	v_add_f32_e32 v63, 1.0, v51
	v_mul_f32_e32 v51, 0xbfb8aa3b, v61
	v_exp_f32_e32 v67, v51
	v_add_f32_e32 v51, 1.0, v62
	v_rcp_f32_e32 v50, v50
	v_rcp_f32_e32 v51, v51
	v_rcp_f32_e32 v62, v63
	v_add_f32_e32 v63, 1.0, v67
	v_rcp_f32_e32 v63, v63
; __device__ __forceinline__ float fast_sigmoid(float x) { return __builtin_amdgcn_rcpf(1.0f + __builtin_amdgcn_exp2f(-1.4426950408889634f * x)); }
; __device__ __forceinline__ u32x4 pack8(const f32x4 a, const f32x4 b) { u32x4 w; w.x = cvt_pk_bf16(a[0], a[1]); w.y = cvt_pk_bf16(a[2], a[3]); w.z = cvt_pk_bf16(b[0], b[1]); w.w = cvt_pk_bf16(b[2], b[3]); return w; }
;     __device__ __forceinline__ void operator()(f32x4 (&acc)[2][2][4][2], const Unit& u, int wr, int wc, int fr, int fq) const {
;     ...
;             for (int ai = 0; ai < 2; ++ai)
; #pragma unroll
;                 for (int m = 0; m < 4; ++m) { const int row = ROWOF(ai, m); const float rs = rsqrtf(rsv[ai * 4 + m] * (1.0f / 2048.0f) + EPS);
;                     f32x4 g0 = acc[ai][0][m][0] * rs, g1 = acc[ai][0][m][1] * rs; const f32x4 u0 = acc[ai][1][m][0] * rs, u1 = acc[ai][1][m][1] * rs;
; #pragma unroll
;                     for (int j = 0; j < 4; ++j) { g0[j] = g0[j] * fast_sigmoid(g0[j]) * u0[j]; g1[j] = g1[j] * fast_sigmoid(g1[j]) * u1[j]; }
;                     *(u32x4*)(P.f_() + (size_t)row * DFF + u.pn * 128 + c8) = pack8(g0, g1); }
	v_pk_mul_f32 v[50:51], v[64:65], v[50:51]
	v_pk_mul_f32 v[56:57], v[56:57], v[66:67] op_sel_hi:[1,0]
	v_pk_mul_f32 v[52:53], v[52:53], v[66:67] op_sel_hi:[1,0]
	v_pk_mul_f32 v[56:57], v[56:57], v[50:51]
	v_pk_mul_f32 v[50:51], v[60:61], v[62:63]
	s_nop 0
	v_pk_mul_f32 v[60:61], v[52:53], v[50:51]
	v_cvt_pk_bf16_f32 v51, v56, v57
	v_fmamk_f32 v56, v149, 0x3a000000, v155
	v_cvt_pk_bf16_f32 v50, v54, v55
	v_mad_i64_i32 v[54:55], s[28:29], v156, s52, v[114:115]
	v_rsq_f32_e32 v56, v56
	v_lshl_add_u64 v[54:55], v[54:55], 0, s[22:23]
	v_cvt_pk_bf16_f32 v52, v58, v59
	v_cvt_pk_bf16_f32 v53, v60, v61
	v_lshl_add_u64 v[54:55], v[54:55], 0, v[134:135]
	global_store_dwordx4 v[54:55], v[50:53], off
	s_nop 1
	v_mov_b32_e32 v50, v56
	v_pk_mul_f32 v[46:47], v[46:47], v[50:51] op_sel_hi:[1,0]
	v_pk_mul_f32 v[42:43], v[42:43], v[50:51] op_sel_hi:[1,0]
	v_pk_mul_f32 v[48:49], v[48:49], v[50:51] op_sel_hi:[1,0]
	v_pk_mul_f32 v[44:45], v[44:45], v[50:51] op_sel_hi:[1,0]
	v_mul_f32_e32 v51, 0xbfb8aa3b, v46
	v_mul_f32_e32 v52, 0xbfb8aa3b, v42
	v_exp_f32_e32 v51, v51
	v_exp_f32_e32 v53, v52
	v_mul_f32_e32 v52, 0xbfb8aa3b, v47
	v_exp_f32_e32 v54, v52
	v_add_f32_e32 v51, 1.0, v51
	v_rcp_f32_e32 v52, v51
	v_add_f32_e32 v51, 1.0, v53
	v_add_f32_e32 v53, 1.0, v54
	v_mul_f32_e32 v54, 0xbfb8aa3b, v43
	v_exp_f32_e32 v55, v54
	v_rcp_f32_e32 v53, v53
	v_rcp_f32_e32 v54, v51
	v_pk_mul_f32 v[38:39], v[38:39], v[50:51] op_sel_hi:[1,0]
	v_add_f32_e32 v51, 1.0, v55
	v_rcp_f32_e32 v55, v51
	v_pk_mul_f32 v[46:47], v[46:47], v[52:53]
	v_pk_mul_f32 v[34:35], v[34:35], v[50:51] op_sel_hi:[1,0]
	v_pk_mul_f32 v[38:39], v[38:39], v[46:47]
	v_mul_f32_e32 v46, 0xbfb8aa3b, v48
	v_pk_mul_f32 v[42:43], v[42:43], v[54:55]
	v_exp_f32_e32 v46, v46
	v_pk_mul_f32 v[42:43], v[34:35], v[42:43]
	v_mul_f32_e32 v35, 0xbfb8aa3b, v44
	v_exp_f32_e32 v35, v35
	v_add_f32_e32 v34, 1.0, v46
	v_mul_f32_e32 v46, 0xbfb8aa3b, v49
	v_exp_f32_e32 v46, v46
	v_add_f32_e32 v47, 1.0, v35
	v_mul_f32_e32 v35, 0xbfb8aa3b, v45
	v_exp_f32_e32 v51, v35
	v_add_f32_e32 v35, 1.0, v46
	v_rcp_f32_e32 v34, v34
	v_rcp_f32_e32 v35, v35
	v_rcp_f32_e32 v46, v47
	v_add_f32_e32 v47, 1.0, v51
	v_rcp_f32_e32 v47, v47
	v_pk_mul_f32 v[34:35], v[48:49], v[34:35]
	v_pk_mul_f32 v[40:41], v[40:41], v[50:51] op_sel_hi:[1,0]
	v_pk_mul_f32 v[36:37], v[36:37], v[50:51] op_sel_hi:[1,0]
	v_pk_mul_f32 v[40:41], v[40:41], v[34:35]
	v_pk_mul_f32 v[34:35], v[44:45], v[46:47]
	v_add_u32_e32 v46, 0x90, v146
	v_pk_mul_f32 v[44:45], v[36:37], v[34:35]
	v_cvt_pk_bf16_f32 v35, v40, v41
	v_fmamk_f32 v40, v148, 0x3a000000, v155
	v_cvt_pk_bf16_f32 v34, v38, v39
	v_mad_i64_i32 v[38:39], s[28:29], v46, s52, v[114:115]
	v_rsq_f32_e32 v40, v40
	v_lshl_add_u64 v[38:39], v[38:39], 0, s[22:23]
	v_cvt_pk_bf16_f32 v36, v42, v43
	v_cvt_pk_bf16_f32 v37, v44, v45
	v_lshl_add_u64 v[38:39], v[38:39], 0, v[134:135]
	global_store_dwordx4 v[38:39], v[34:37], off
	s_nop 1
	v_mov_b32_e32 v34, v40
	v_pk_mul_f32 v[30:31], v[30:31], v[34:35] op_sel_hi:[1,0]
	v_pk_mul_f32 v[26:27], v[26:27], v[34:35] op_sel_hi:[1,0]
	v_pk_mul_f32 v[32:33], v[32:33], v[34:35] op_sel_hi:[1,0]
	v_pk_mul_f32 v[28:29], v[28:29], v[34:35] op_sel_hi:[1,0]
	v_mul_f32_e32 v35, 0xbfb8aa3b, v30
	v_mul_f32_e32 v36, 0xbfb8aa3b, v26
	v_exp_f32_e32 v35, v35
	v_exp_f32_e32 v37, v36
	v_mul_f32_e32 v36, 0xbfb8aa3b, v31
	v_exp_f32_e32 v38, v36
	v_add_f32_e32 v35, 1.0, v35
	v_rcp_f32_e32 v36, v35
	v_add_f32_e32 v35, 1.0, v37
	v_add_f32_e32 v37, 1.0, v38
	v_mul_f32_e32 v38, 0xbfb8aa3b, v27
	v_exp_f32_e32 v39, v38
	v_rcp_f32_e32 v37, v37
	v_rcp_f32_e32 v38, v35
	v_pk_mul_f32 v[22:23], v[22:23], v[34:35] op_sel_hi:[1,0]
	v_add_f32_e32 v35, 1.0, v39
; __device__ __forceinline__ float fast_sigmoid(float x) { return __builtin_amdgcn_rcpf(1.0f + __builtin_amdgcn_exp2f(-1.4426950408889634f * x)); }
; __device__ __forceinline__ u32x4 pack8(const f32x4 a, const f32x4 b) { u32x4 w; w.x = cvt_pk_bf16(a[0], a[1]); w.y = cvt_pk_bf16(a[2], a[3]); w.z = cvt_pk_bf16(b[0], b[1]); w.w = cvt_pk_bf16(b[2], b[3]); return w; }
;     __device__ __forceinline__ void operator()(f32x4 (&acc)[2][2][4][2], const Unit& u, int wr, int wc, int fr, int fq) const {
;     ...
;             for (int ai = 0; ai < 2; ++ai)
; #pragma unroll
;                 for (int m = 0; m < 4; ++m) { const int row = ROWOF(ai, m); const float rs = rsqrtf(rsv[ai * 4 + m] * (1.0f / 2048.0f) + EPS);
;                     f32x4 g0 = acc[ai][0][m][0] * rs, g1 = acc[ai][0][m][1] * rs; const f32x4 u0 = acc[ai][1][m][0] * rs, u1 = acc[ai][1][m][1] * rs;
; #pragma unroll
;                     for (int j = 0; j < 4; ++j) { g0[j] = g0[j] * fast_sigmoid(g0[j]) * u0[j]; g1[j] = g1[j] * fast_sigmoid(g1[j]) * u1[j]; }
;                     *(u32x4*)(P.f_() + (size_t)row * DFF + u.pn * 128 + c8) = pack8(g0, g1); }
	v_rcp_f32_e32 v39, v35
	v_pk_mul_f32 v[30:31], v[30:31], v[36:37]
	v_pk_mul_f32 v[18:19], v[18:19], v[34:35] op_sel_hi:[1,0]
	v_pk_mul_f32 v[22:23], v[22:23], v[30:31]
	v_mul_f32_e32 v30, 0xbfb8aa3b, v32
	v_pk_mul_f32 v[26:27], v[26:27], v[38:39]
	v_exp_f32_e32 v30, v30
	v_pk_mul_f32 v[26:27], v[18:19], v[26:27]
	v_mul_f32_e32 v19, 0xbfb8aa3b, v28
	v_exp_f32_e32 v19, v19
	v_add_f32_e32 v18, 1.0, v30
	v_mul_f32_e32 v30, 0xbfb8aa3b, v33
	v_exp_f32_e32 v30, v30
	v_add_f32_e32 v31, 1.0, v19
	v_mul_f32_e32 v19, 0xbfb8aa3b, v29
	v_exp_f32_e32 v35, v19
	v_add_f32_e32 v19, 1.0, v30
	v_rcp_f32_e32 v18, v18
	v_rcp_f32_e32 v19, v19
	v_rcp_f32_e32 v30, v31
	v_add_f32_e32 v31, 1.0, v35
	v_rcp_f32_e32 v31, v31
	v_pk_mul_f32 v[18:19], v[32:33], v[18:19]
	v_pk_mul_f32 v[24:25], v[24:25], v[34:35] op_sel_hi:[1,0]
	v_pk_mul_f32 v[20:21], v[20:21], v[34:35] op_sel_hi:[1,0]
	v_pk_mul_f32 v[24:25], v[24:25], v[18:19]
	v_pk_mul_f32 v[18:19], v[28:29], v[30:31]
	v_add_u32_e32 v30, 0xa0, v146
	v_pk_mul_f32 v[28:29], v[20:21], v[18:19]
	v_cvt_pk_bf16_f32 v19, v24, v25
	v_fmamk_f32 v24, v147, 0x3a000000, v155
	v_cvt_pk_bf16_f32 v18, v22, v23
	v_mad_i64_i32 v[22:23], s[28:29], v30, s52, v[114:115]
	v_rsq_f32_e32 v24, v24
	v_lshl_add_u64 v[22:23], v[22:23], 0, s[22:23]
	v_cvt_pk_bf16_f32 v20, v26, v27
	v_cvt_pk_bf16_f32 v21, v28, v29
	v_lshl_add_u64 v[22:23], v[22:23], 0, v[134:135]
	global_store_dwordx4 v[22:23], v[18:21], off
	s_nop 1
	v_mov_b32_e32 v18, v24
	v_pk_mul_f32 v[14:15], v[14:15], v[18:19] op_sel_hi:[1,0]
	v_pk_mul_f32 v[10:11], v[10:11], v[18:19] op_sel_hi:[1,0]
	v_pk_mul_f32 v[16:17], v[16:17], v[18:19] op_sel_hi:[1,0]
	v_pk_mul_f32 v[12:13], v[12:13], v[18:19] op_sel_hi:[1,0]
	v_mul_f32_e32 v19, 0xbfb8aa3b, v14
	v_mul_f32_e32 v20, 0xbfb8aa3b, v10
	v_exp_f32_e32 v19, v19
	v_exp_f32_e32 v21, v20
	v_mul_f32_e32 v20, 0xbfb8aa3b, v15
	v_exp_f32_e32 v22, v20
	v_add_f32_e32 v19, 1.0, v19
	v_rcp_f32_e32 v20, v19
	v_add_f32_e32 v19, 1.0, v21
	v_add_f32_e32 v21, 1.0, v22
	v_mul_f32_e32 v22, 0xbfb8aa3b, v11
	v_exp_f32_e32 v23, v22
	v_rcp_f32_e32 v21, v21
	v_rcp_f32_e32 v22, v19
	v_pk_mul_f32 v[6:7], v[6:7], v[18:19] op_sel_hi:[1,0]
	v_add_f32_e32 v19, 1.0, v23
	v_rcp_f32_e32 v23, v19
	v_pk_mul_f32 v[14:15], v[14:15], v[20:21]
	v_pk_mul_f32 v[2:3], v[2:3], v[18:19] op_sel_hi:[1,0]
	v_pk_mul_f32 v[6:7], v[6:7], v[14:15]
	v_mul_f32_e32 v14, 0xbfb8aa3b, v16
	v_pk_mul_f32 v[10:11], v[10:11], v[22:23]
	v_exp_f32_e32 v14, v14
	v_pk_mul_f32 v[10:11], v[2:3], v[10:11]
	v_mul_f32_e32 v3, 0xbfb8aa3b, v12
	v_exp_f32_e32 v3, v3
	v_add_f32_e32 v2, 1.0, v14
	v_mul_f32_e32 v14, 0xbfb8aa3b, v17
	v_exp_f32_e32 v14, v14
	v_add_f32_e32 v15, 1.0, v3
	v_mul_f32_e32 v3, 0xbfb8aa3b, v13
	v_exp_f32_e32 v19, v3
	v_add_f32_e32 v3, 1.0, v14
	v_rcp_f32_e32 v2, v2
	v_rcp_f32_e32 v3, v3
	v_rcp_f32_e32 v14, v15
	v_add_f32_e32 v15, 1.0, v19
	v_rcp_f32_e32 v15, v15
	v_pk_mul_f32 v[2:3], v[16:17], v[2:3]
	v_pk_mul_f32 v[8:9], v[8:9], v[18:19] op_sel_hi:[1,0]
	v_pk_mul_f32 v[4:5], v[4:5], v[18:19] op_sel_hi:[1,0]
	v_pk_mul_f32 v[8:9], v[8:9], v[2:3]
	v_pk_mul_f32 v[2:3], v[12:13], v[14:15]
	v_add_u32_e32 v14, 0xb0, v146
	v_pk_mul_f32 v[12:13], v[4:5], v[2:3]
	v_cvt_pk_bf16_f32 v2, v6, v7
	v_mad_i64_i32 v[6:7], s[28:29], v14, s52, v[114:115]
	v_lshl_add_u64 v[6:7], v[6:7], 0, s[22:23]
	v_cvt_pk_bf16_f32 v3, v8, v9
	v_cvt_pk_bf16_f32 v4, v10, v11
	v_cvt_pk_bf16_f32 v5, v12, v13
	v_lshl_add_u64 v[6:7], v[6:7], 0, v[134:135]
	s_andn2_b64 vcc, exec, s[18:19]
	s_mov_b64 s[18:19], -1
	global_store_dwordx4 v[6:7], v[2:5], off
	s_cbranch_vccnz .LBB0_995
	s_andn2_b64 vcc, exec, s[4:5]
	s_cbranch_vccnz .LBB0_994
	s_barrier
	s_branch .LBB0_994

;     __device__ __forceinline__ void fused(f32x4 (&acc)[2][2][4][2], const Unit& u, int wr, int wc, int fr, int fq, LAS unsigned char* lds, int wid, int lane) const {
;     ...
;         __syncthreads();
;         if (tid < 256) { float tot = 0.f;
; #pragma unroll
;             for (int t = 0; t < 8; ++t) tot += __uint_as_float(__hip_atomic_load((unsigned*)(xb_ + t * 256 + tid), __ATOMIC_RELAXED, __HIP_MEMORY_SCOPE_AGENT));
;             Sl[tid] = rsqrtf(tot * (1.0f / DM) + EPS); }
.LBB0_1109:
	s_barrier
	s_and_saveexec_b64 s[12:13], s[0:1]
	s_cbranch_execz .LBB0_1111
	v_mov_b32_e32 v187, 0
	global_load_dword v1, v186, s[10:11] sc1
	global_load_dword v148, v186, s[10:11] offset:1024 sc1
	global_load_dword v149, v186, s[10:11] offset:2048 sc1
	global_load_dword v150, v186, s[10:11] offset:3072 sc1
	v_lshl_add_u64 v[146:147], s[10:11], 0, v[186:187]
	v_add_co_u32_e32 v146, vcc, 0x1000, v146
	s_mov_b32 s0, 0x800000
	s_nop 0
	v_addc_co_u32_e32 v147, vcc, 0, v147, vcc
	global_load_dword v151, v[146:147], off sc1
	global_load_dword v152, v[146:147], off offset:1024 sc1
	global_load_dword v153, v[146:147], off offset:2048 sc1
	s_nop 0
	global_load_dword v146, v[146:147], off offset:3072 sc1
	v_mov_b32_e32 v147, 0x358637bd
	s_waitcnt vmcnt(7)
	v_add_f32_e32 v1, 0, v1
	s_waitcnt vmcnt(6)
	v_add_f32_e32 v1, v1, v148
	s_waitcnt vmcnt(5)
	v_add_f32_e32 v1, v1, v149
	s_waitcnt vmcnt(4)
	v_add_f32_e32 v1, v1, v150
	s_waitcnt vmcnt(3)
	v_add_f32_e32 v1, v1, v151
	s_waitcnt vmcnt(2)
	v_add_f32_e32 v1, v1, v152
	s_waitcnt vmcnt(1)
	v_add_f32_e32 v1, v1, v153
	s_waitcnt vmcnt(0)
	v_add_f32_e32 v1, v1, v146
	v_fmac_f32_e32 v147, 0x3a000000, v1
	s_nop 1
	v_rsq_f32_e32 v1, v147
	s_nop 0
	v_add_u32_e32 v146, 0, v186
	ds_write_b32 v146, v1 offset:4096
